# logits: wf stored by P0 directly as the MFMA B-fragment image; logits block reads it with coalesced loads (no LDS image build, one barrier less)
# speedup vs baseline: 1.0027x; 1.0027x over previous
; __global__ void __launch_bounds__(NWAVES * 64, 2) fwd_megakernel(Args args) {
;     ...
;         for (long i = gt; i < (long)NH * DM; i += NGT) { const int h = (int)(i / DM), k = (int)(i % DM); wf[i] = args.in[6][k] * args.in[7][(size_t)k * DIN + 3072 + h]; }
.LBB0_151:
	v_ashrrev_i32_e32 v4, 31, v17
	v_lshrrev_b32_e32 v4, 21, v4
	v_lshl_add_u64 v[8:9], v[16:17], 0, v[4:5]
	v_ashrrev_i64 v[8:9], 11, v[8:9]
	v_lshlrev_b64 v[10:11], 13, v[8:9]
	v_mov_b32_e32 v6, v5
	v_mov_b32_e32 v7, v8
	v_mad_u64_u32 v[12:13], s[16:17], v8, s1, 0
	v_sub_co_u32_e32 v10, vcc, v2, v10
	v_ashrrev_i64 v[6:7], 30, v[6:7]
	s_nop 0
	v_subb_co_u32_e32 v11, vcc, v3, v11, vcc
	v_mov_b32_e32 v4, v13
	v_mad_u64_u32 v[8:9], s[16:17], v9, s1, v[4:5]
	v_sub_co_u32_e32 v6, vcc, v6, v12
	v_lshl_add_u64 v[10:11], s[20:21], 0, v[10:11]
	s_nop 0
	v_subb_co_u32_e32 v7, vcc, v7, v8, vcc
	v_lshl_add_u64 v[6:7], v[0:1], 0, v[6:7]
	global_load_dword v4, v[10:11], off
	global_load_dword v8, v[6:7], off
	v_lshl_add_u64 v[16:17], v[16:17], 0, s[8:9]
	v_cmp_lt_i64_e32 vcc, s[14:15], v[16:17]
	v_lshrrev_b32_e32 v40, 2, v2
	v_and_b32_e32 v41, 0x7ff, v40
	v_lshrrev_b32_e32 v42, 11, v40
	v_lshrrev_b32_e32 v43, 7, v41
	v_lshlrev_b32_e32 v43, 10, v43
	v_bfe_u32 v44, v41, 3, 4
	v_lshl_or_b32 v43, v44, 4, v43
	v_bfe_u32 v44, v41, 2, 1
	v_lshl_or_b32 v43, v44, 8, v43
	v_and_b32_e32 v44, 3, v41
	v_or_b32_e32 v43, v43, v44
	v_lshrrev_b32_e32 v44, 2, v42
	v_lshl_or_b32 v43, v44, 9, v43
	v_and_b32_e32 v44, 3, v42
	v_lshl_or_b32 v43, v44, 2, v43
	v_lshlrev_b32_e32 v44, 2, v43
	v_mov_b32_e32 v45, 0
	v_lshl_add_u64 v[6:7], s[38:39], 0, v[44:45]
	s_or_b64 s[12:13], vcc, s[12:13]
	v_lshl_add_u64 v[2:3], v[2:3], 0, s[10:11]
	v_lshl_add_u64 v[0:1], v[0:1], 0, s[6:7]
	s_waitcnt vmcnt(0)
	v_mul_f32_e32 v4, v4, v8
	global_store_dword v[6:7], v4, off
	s_andn2_b64 exec, exec, s[12:13]
	s_cbranch_execnz .LBB0_151

; __device__ __forceinline__ int opaque_tid() { int t = threadIdx.x; asm volatile("" : "+v"(t)); return t; }
; __global__ void __launch_bounds__(NWAVES * 64, 2) fwd_megakernel(Args args) {
;     ...
;         if (j == 2) {
;             const int ln = opaque_tid() & 63;
;             float wreg[32];
; #pragma unroll
;             for (int jj = 0; jj < 4; ++jj) { const f32x4 a = *(const f32x4*)(wf + (size_t)wave * DM + 512 * jj + 8 * ln), bq = *(const f32x4*)(wf + (size_t)wave * DM + 512 * jj + 8 * ln + 4);
; #pragma unroll
;                 for (int e = 0; e < 4; ++e) { wreg[8 * jj + e] = a[e]; wreg[8 * jj + 4 + e] = bq[e]; } }
;             const float bf = args.in[8][wave];
;             for (int m0 = vcu2 * 4; m0 < M; m0 += G * 4) {
;                 u32x4 pw[4][4]; float sq[4];
; #pragma unroll
;                 for (int q = 0; q < 4; ++q) { sq[q] = ss[M + m0 + q];
; #pragma unroll
;                     for (int jj = 0; jj < 4; ++jj) pw[q][jj] = *(const u32x4*)(XB + (size_t)(m0 + q) * DM + 512 * jj + 8 * ln); }
; #pragma unroll
;                 for (int q = 0; q < 4; ++q) { float d = 0.f;
; #pragma unroll
;                     for (int jj = 0; jj < 4; ++jj) { const u32x4 w = pw[q][jj];
;                         d += __uint_as_float(w.x << 16) * wreg[8 * jj + 0] + __uint_as_float(w.x & 0xffff0000u) * wreg[8 * jj + 1] + __uint_as_float(w.y << 16) * wreg[8 * jj + 2] + __uint_as_float(w.y & 0xffff0000u) * wreg[8 * jj + 3]
;                            + __uint_as_float(w.z << 16) * wreg[8 * jj + 4] + __uint_as_float(w.z & 0xffff0000u) * wreg[8 * jj + 5] + __uint_as_float(w.w << 16) * wreg[8 * jj + 6] + __uint_as_float(w.w & 0xffff0000u) * wreg[8 * jj + 7]; }
.LBB0_591:
	s_and_b64 vcc, exec, s[4:5]
	s_cbranch_vccz .LBB0_605
	s_cmp_gt_i32 s39, 1
	s_cbranch_scc0 .LBB0_606
	s_cmp_lt_i32 s39, 3
	s_mov_b64 s[4:5], -1
	s_cbranch_scc0 .LBB0_607
	v_lshrrev_b32_e32 v0, 6, v166
	v_readlane_b32 s4, v249, 1
	v_readfirstlane_b32 s12, v0
	s_lshl_b32 s4, s4, 4
	s_cmpk_gt_i32 s4, 0x3fff
	s_cbranch_scc1 .Llg_done
	s_add_u32 s8, s60, 0x100000
	s_addc_u32 s9, s61, 0
	v_and_b32_e32 v5, 3, v168
	v_lshrrev_b32_e32 v6, 2, v168
	v_lshlrev_b32_e32 v5, 12, v5
	v_lshl_or_b32 v2, v6, 4, v5
	v_lshlrev_b32_e32 v3, 4, v168
	v_add_u32_e32 v132, 0x4000, v2
	v_readlane_b32 s16, v250, 63
	v_readlane_b32 s17, v249, 0
	s_lshl_b32 s5, s12, 2
	s_sub_u32 s16, s16, s5
	s_subb_u32 s17, s17, 0
	s_mov_b32 s18, 0xbfb8aa3b
	s_mov_b32 s19, 0x3f317218
.Llg_trip:
	s_lshl_b32 s5, s12, 3
	s_add_u32 s5, s5, s4
	s_lshl_b32 s5, s5, 12
	s_add_u32 s6, s94, s5
	s_addc_u32 s7, s95, 0
	s_lshr_b32 s13, s4, 6
	s_lshl_b32 s1, s12, 1
	s_add_i32 s13, s13, s1
	v_mov_b32_e32 v4, 0
	v_mov_b32_e32 v5, 0
	v_mov_b32_e32 v6, 0
	v_mov_b32_e32 v7, 0
	v_mov_b32_e32 v8, 0
	v_mov_b32_e32 v9, 0
	v_mov_b32_e32 v10, 0
	v_mov_b32_e32 v11, 0
	v_mov_b32_e32 v12, 0
	v_mov_b32_e32 v13, 0
	v_mov_b32_e32 v14, 0
	v_mov_b32_e32 v15, 0
	v_mov_b32_e32 v16, 0
	v_mov_b32_e32 v17, 0
	v_mov_b32_e32 v18, 0
	v_mov_b32_e32 v19, 0
	s_add_i32 s1, s13, 0
	s_and_b32 s1, s1, 15
	s_lshl_b32 s1, s1, 8
	s_add_u32 s10, s6, s1
	s_addc_u32 s11, s7, 0
	global_load_dwordx4 v[36:39], v2, s[10:11]
	global_load_dwordx4 v[40:43], v132, s[10:11]
	s_add_i32 s1, s13, 1
	s_and_b32 s1, s1, 15
	s_lshl_b32 s1, s1, 8
	s_add_u32 s10, s6, s1
	s_addc_u32 s11, s7, 0
	global_load_dwordx4 v[44:47], v2, s[10:11]
	global_load_dwordx4 v[48:51], v132, s[10:11]
	s_add_i32 s1, s13, 2
	s_and_b32 s1, s1, 15
	s_lshl_b32 s1, s1, 8
	s_add_u32 s10, s6, s1
	s_addc_u32 s11, s7, 0
	global_load_dwordx4 v[52:55], v2, s[10:11]
	global_load_dwordx4 v[56:59], v132, s[10:11]
	s_add_i32 s1, s13, 3
	s_and_b32 s1, s1, 15
	s_lshl_b32 s1, s1, 8
	s_add_u32 s10, s6, s1
	s_addc_u32 s11, s7, 0
	global_load_dwordx4 v[60:63], v2, s[10:11]
	global_load_dwordx4 v[64:67], v132, s[10:11]
	s_add_i32 s1, s13, 4
	s_and_b32 s1, s1, 15
	s_lshl_b32 s1, s1, 8
	s_add_u32 s10, s6, s1
	s_addc_u32 s11, s7, 0
	global_load_dwordx4 v[68:71], v2, s[10:11]
	global_load_dwordx4 v[72:75], v132, s[10:11]
	s_add_i32 s1, s13, 0
	s_and_b32 s1, s1, 15
	s_lshl_b32 s1, s1, 12
	s_add_u32 s36, s8, s1
	s_addc_u32 s37, s9, 0
	global_load_dwordx4 v[84:87], v3, s[36:37] offset:0
	global_load_dwordx4 v[88:91], v3, s[36:37] offset:1024
	global_load_dwordx4 v[92:95], v3, s[36:37] offset:2048
	global_load_dwordx4 v[96:99], v3, s[36:37] offset:3072
	s_add_i32 s1, s13, 1
	s_and_b32 s1, s1, 15
	s_lshl_b32 s1, s1, 12
	s_add_u32 s36, s8, s1
	s_addc_u32 s37, s9, 0
	global_load_dwordx4 v[100:103], v3, s[36:37] offset:0
	global_load_dwordx4 v[104:107], v3, s[36:37] offset:1024
	global_load_dwordx4 v[108:111], v3, s[36:37] offset:2048
	global_load_dwordx4 v[112:115], v3, s[36:37] offset:3072
	s_waitcnt vmcnt(16)
	v_lshlrev_b32_e32 v20, 16, v36
	v_and_b32_e32 v36, 0xffff0000, v36
	v_lshlrev_b32_e32 v21, 16, v37
	v_and_b32_e32 v37, 0xffff0000, v37
	v_lshlrev_b32_e32 v22, 16, v38
	v_and_b32_e32 v38, 0xffff0000, v38
	v_lshlrev_b32_e32 v23, 16, v39
	v_and_b32_e32 v39, 0xffff0000, v39
	v_lshlrev_b32_e32 v24, 16, v40
	v_and_b32_e32 v40, 0xffff0000, v40
	v_lshlrev_b32_e32 v25, 16, v41
	v_and_b32_e32 v41, 0xffff0000, v41
	v_lshlrev_b32_e32 v26, 16, v42
	v_and_b32_e32 v42, 0xffff0000, v42
	v_lshlrev_b32_e32 v27, 16, v43
	v_and_b32_e32 v43, 0xffff0000, v43
	s_add_i32 s1, s13, 5
	s_and_b32 s1, s1, 15
	s_lshl_b32 s1, s1, 8
	s_add_u32 s10, s6, s1
	s_addc_u32 s11, s7, 0
	global_load_dwordx4 v[76:79], v2, s[10:11]
	global_load_dwordx4 v[80:83], v132, s[10:11]
	s_add_i32 s1, s13, 2
	s_and_b32 s1, s1, 15
	s_lshl_b32 s1, s1, 12
	s_add_u32 s36, s8, s1
	s_addc_u32 s37, s9, 0
	global_load_dwordx4 v[116:119], v3, s[36:37] offset:0
	global_load_dwordx4 v[120:123], v3, s[36:37] offset:1024
	global_load_dwordx4 v[124:127], v3, s[36:37] offset:2048
	global_load_dwordx4 v[128:131], v3, s[36:37] offset:3072
	s_waitcnt vmcnt(10)
	v_mfma_f32_4x4x1_16b_f32 v[4:7], v20, v84, v[4:7]
	v_mfma_f32_4x4x1_16b_f32 v[8:11], v20, v92, v[8:11]
	v_lshlrev_b32_e32 v28, 16, v44
	v_mfma_f32_4x4x1_16b_f32 v[12:15], v24, v84, v[12:15]
	v_mfma_f32_4x4x1_16b_f32 v[16:19], v24, v92, v[16:19]
	v_and_b32_e32 v44, 0xffff0000, v44
	v_mfma_f32_4x4x1_16b_f32 v[4:7], v36, v85, v[4:7]
	v_mfma_f32_4x4x1_16b_f32 v[8:11], v36, v93, v[8:11]
	v_lshlrev_b32_e32 v29, 16, v45
	v_mfma_f32_4x4x1_16b_f32 v[12:15], v40, v85, v[12:15]
	v_mfma_f32_4x4x1_16b_f32 v[16:19], v40, v93, v[16:19]
	v_and_b32_e32 v45, 0xffff0000, v45
	v_mfma_f32_4x4x1_16b_f32 v[4:7], v21, v86, v[4:7]
	v_mfma_f32_4x4x1_16b_f32 v[8:11], v21, v94, v[8:11]
	v_lshlrev_b32_e32 v30, 16, v46
	v_mfma_f32_4x4x1_16b_f32 v[12:15], v25, v86, v[12:15]
	v_mfma_f32_4x4x1_16b_f32 v[16:19], v25, v94, v[16:19]
	v_and_b32_e32 v46, 0xffff0000, v46
	v_mfma_f32_4x4x1_16b_f32 v[4:7], v37, v87, v[4:7]
	v_mfma_f32_4x4x1_16b_f32 v[8:11], v37, v95, v[8:11]
	v_lshlrev_b32_e32 v31, 16, v47
	v_mfma_f32_4x4x1_16b_f32 v[12:15], v41, v87, v[12:15]
	v_mfma_f32_4x4x1_16b_f32 v[16:19], v41, v95, v[16:19]
	v_and_b32_e32 v47, 0xffff0000, v47
	v_mfma_f32_4x4x1_16b_f32 v[4:7], v22, v88, v[4:7]
	v_mfma_f32_4x4x1_16b_f32 v[8:11], v22, v96, v[8:11]
	v_lshlrev_b32_e32 v32, 16, v48
	v_mfma_f32_4x4x1_16b_f32 v[12:15], v26, v88, v[12:15]
	v_mfma_f32_4x4x1_16b_f32 v[16:19], v26, v96, v[16:19]
	v_and_b32_e32 v48, 0xffff0000, v48
	v_mfma_f32_4x4x1_16b_f32 v[4:7], v38, v89, v[4:7]
	v_mfma_f32_4x4x1_16b_f32 v[8:11], v38, v97, v[8:11]
	v_lshlrev_b32_e32 v33, 16, v49
	v_mfma_f32_4x4x1_16b_f32 v[12:15], v42, v89, v[12:15]
	v_mfma_f32_4x4x1_16b_f32 v[16:19], v42, v97, v[16:19]
	v_and_b32_e32 v49, 0xffff0000, v49
	v_mfma_f32_4x4x1_16b_f32 v[4:7], v23, v90, v[4:7]
	v_mfma_f32_4x4x1_16b_f32 v[8:11], v23, v98, v[8:11]
	v_lshlrev_b32_e32 v34, 16, v50
	v_mfma_f32_4x4x1_16b_f32 v[12:15], v27, v90, v[12:15]
	v_mfma_f32_4x4x1_16b_f32 v[16:19], v27, v98, v[16:19]
	v_and_b32_e32 v50, 0xffff0000, v50
	v_mfma_f32_4x4x1_16b_f32 v[4:7], v39, v91, v[4:7]
	v_mfma_f32_4x4x1_16b_f32 v[8:11], v39, v99, v[8:11]
	v_lshlrev_b32_e32 v35, 16, v51
	v_mfma_f32_4x4x1_16b_f32 v[12:15], v43, v91, v[12:15]
	v_mfma_f32_4x4x1_16b_f32 v[16:19], v43, v99, v[16:19]
	v_and_b32_e32 v51, 0xffff0000, v51
	s_add_i32 s1, s13, 6
	s_and_b32 s1, s1, 15
	s_lshl_b32 s1, s1, 8
	s_add_u32 s10, s6, s1
	s_addc_u32 s11, s7, 0
	global_load_dwordx4 v[36:39], v2, s[10:11]
	global_load_dwordx4 v[40:43], v132, s[10:11]
	s_add_i32 s1, s13, 3
	s_and_b32 s1, s1, 15
	s_lshl_b32 s1, s1, 12
	s_add_u32 s36, s8, s1
	s_addc_u32 s37, s9, 0
	global_load_dwordx4 v[84:87], v3, s[36:37] offset:0
	global_load_dwordx4 v[88:91], v3, s[36:37] offset:1024
	global_load_dwordx4 v[92:95], v3, s[36:37] offset:2048
	global_load_dwordx4 v[96:99], v3, s[36:37] offset:3072
	s_waitcnt vmcnt(12)
; __global__ void __launch_bounds__(NWAVES * 64, 2) fwd_megakernel(Args args) {
;     ...
;                     for (int jj = 0; jj < 4; ++jj) pw[q][jj] = *(const u32x4*)(XB + (size_t)(m0 + q) * DM + 512 * jj + 8 * ln); }
; #pragma unroll
;                 for (int q = 0; q < 4; ++q) { float d = 0.f;
; #pragma unroll
;                     for (int jj = 0; jj < 4; ++jj) { const u32x4 w = pw[q][jj];
;                         d += __uint_as_float(w.x << 16) * wreg[8 * jj + 0] + __uint_as_float(w.x & 0xffff0000u) * wreg[8 * jj + 1] + __uint_as_float(w.y << 16) * wreg[8 * jj + 2] + __uint_as_float(w.y & 0xffff0000u) * wreg[8 * jj + 3]
;                            + __uint_as_float(w.z << 16) * wreg[8 * jj + 4] + __uint_as_float(w.z & 0xffff0000u) * wreg[8 * jj + 5] + __uint_as_float(w.w << 16) * wreg[8 * jj + 6] + __uint_as_float(w.w & 0xffff0000u) * wreg[8 * jj + 7]; }
	v_mfma_f32_4x4x1_16b_f32 v[4:7], v28, v100, v[4:7]
	v_mfma_f32_4x4x1_16b_f32 v[8:11], v28, v108, v[8:11]
	v_lshlrev_b32_e32 v20, 16, v52
	v_mfma_f32_4x4x1_16b_f32 v[12:15], v32, v100, v[12:15]
	v_mfma_f32_4x4x1_16b_f32 v[16:19], v32, v108, v[16:19]
	v_and_b32_e32 v52, 0xffff0000, v52
	v_mfma_f32_4x4x1_16b_f32 v[4:7], v44, v101, v[4:7]
	v_mfma_f32_4x4x1_16b_f32 v[8:11], v44, v109, v[8:11]
	v_lshlrev_b32_e32 v21, 16, v53
	v_mfma_f32_4x4x1_16b_f32 v[12:15], v48, v101, v[12:15]
	v_mfma_f32_4x4x1_16b_f32 v[16:19], v48, v109, v[16:19]
	v_and_b32_e32 v53, 0xffff0000, v53
	v_mfma_f32_4x4x1_16b_f32 v[4:7], v29, v102, v[4:7]
	v_mfma_f32_4x4x1_16b_f32 v[8:11], v29, v110, v[8:11]
	v_lshlrev_b32_e32 v22, 16, v54
	v_mfma_f32_4x4x1_16b_f32 v[12:15], v33, v102, v[12:15]
	v_mfma_f32_4x4x1_16b_f32 v[16:19], v33, v110, v[16:19]
	v_and_b32_e32 v54, 0xffff0000, v54
	v_mfma_f32_4x4x1_16b_f32 v[4:7], v45, v103, v[4:7]
	v_mfma_f32_4x4x1_16b_f32 v[8:11], v45, v111, v[8:11]
	v_lshlrev_b32_e32 v23, 16, v55
	v_mfma_f32_4x4x1_16b_f32 v[12:15], v49, v103, v[12:15]
	v_mfma_f32_4x4x1_16b_f32 v[16:19], v49, v111, v[16:19]
	v_and_b32_e32 v55, 0xffff0000, v55
	v_mfma_f32_4x4x1_16b_f32 v[4:7], v30, v104, v[4:7]
	v_mfma_f32_4x4x1_16b_f32 v[8:11], v30, v112, v[8:11]
	v_lshlrev_b32_e32 v24, 16, v56
	v_mfma_f32_4x4x1_16b_f32 v[12:15], v34, v104, v[12:15]
	v_mfma_f32_4x4x1_16b_f32 v[16:19], v34, v112, v[16:19]
	v_and_b32_e32 v56, 0xffff0000, v56
	v_mfma_f32_4x4x1_16b_f32 v[4:7], v46, v105, v[4:7]
	v_mfma_f32_4x4x1_16b_f32 v[8:11], v46, v113, v[8:11]
	v_lshlrev_b32_e32 v25, 16, v57
	v_mfma_f32_4x4x1_16b_f32 v[12:15], v50, v105, v[12:15]
	v_mfma_f32_4x4x1_16b_f32 v[16:19], v50, v113, v[16:19]
	v_and_b32_e32 v57, 0xffff0000, v57
	v_mfma_f32_4x4x1_16b_f32 v[4:7], v31, v106, v[4:7]
	v_mfma_f32_4x4x1_16b_f32 v[8:11], v31, v114, v[8:11]
	v_lshlrev_b32_e32 v26, 16, v58
	v_mfma_f32_4x4x1_16b_f32 v[12:15], v35, v106, v[12:15]
	v_mfma_f32_4x4x1_16b_f32 v[16:19], v35, v114, v[16:19]
	v_and_b32_e32 v58, 0xffff0000, v58
	v_mfma_f32_4x4x1_16b_f32 v[4:7], v47, v107, v[4:7]
	v_mfma_f32_4x4x1_16b_f32 v[8:11], v47, v115, v[8:11]
	v_lshlrev_b32_e32 v27, 16, v59
	v_mfma_f32_4x4x1_16b_f32 v[12:15], v51, v107, v[12:15]
	v_mfma_f32_4x4x1_16b_f32 v[16:19], v51, v115, v[16:19]
	v_and_b32_e32 v59, 0xffff0000, v59
	s_add_i32 s1, s13, 7
	s_and_b32 s1, s1, 15
	s_lshl_b32 s1, s1, 8
	s_add_u32 s10, s6, s1
	s_addc_u32 s11, s7, 0
	global_load_dwordx4 v[44:47], v2, s[10:11]
	global_load_dwordx4 v[48:51], v132, s[10:11]
	s_add_i32 s1, s13, 4
	s_and_b32 s1, s1, 15
	s_lshl_b32 s1, s1, 12
	s_add_u32 s36, s8, s1
	s_addc_u32 s37, s9, 0
	global_load_dwordx4 v[100:103], v3, s[36:37] offset:0
	global_load_dwordx4 v[104:107], v3, s[36:37] offset:1024
	global_load_dwordx4 v[108:111], v3, s[36:37] offset:2048
	global_load_dwordx4 v[112:115], v3, s[36:37] offset:3072
	s_waitcnt vmcnt(12)
	v_mfma_f32_4x4x1_16b_f32 v[4:7], v20, v116, v[4:7]
	v_mfma_f32_4x4x1_16b_f32 v[8:11], v20, v124, v[8:11]
	v_lshlrev_b32_e32 v28, 16, v60
	v_mfma_f32_4x4x1_16b_f32 v[12:15], v24, v116, v[12:15]
	v_mfma_f32_4x4x1_16b_f32 v[16:19], v24, v124, v[16:19]
	v_and_b32_e32 v60, 0xffff0000, v60
	v_mfma_f32_4x4x1_16b_f32 v[4:7], v52, v117, v[4:7]
	v_mfma_f32_4x4x1_16b_f32 v[8:11], v52, v125, v[8:11]
	v_lshlrev_b32_e32 v29, 16, v61
	v_mfma_f32_4x4x1_16b_f32 v[12:15], v56, v117, v[12:15]
	v_mfma_f32_4x4x1_16b_f32 v[16:19], v56, v125, v[16:19]
	v_and_b32_e32 v61, 0xffff0000, v61
	v_mfma_f32_4x4x1_16b_f32 v[4:7], v21, v118, v[4:7]
	v_mfma_f32_4x4x1_16b_f32 v[8:11], v21, v126, v[8:11]
	v_lshlrev_b32_e32 v30, 16, v62
	v_mfma_f32_4x4x1_16b_f32 v[12:15], v25, v118, v[12:15]
	v_mfma_f32_4x4x1_16b_f32 v[16:19], v25, v126, v[16:19]
	v_and_b32_e32 v62, 0xffff0000, v62
	v_mfma_f32_4x4x1_16b_f32 v[4:7], v53, v119, v[4:7]
	v_mfma_f32_4x4x1_16b_f32 v[8:11], v53, v127, v[8:11]
	v_lshlrev_b32_e32 v31, 16, v63
	v_mfma_f32_4x4x1_16b_f32 v[12:15], v57, v119, v[12:15]
	v_mfma_f32_4x4x1_16b_f32 v[16:19], v57, v127, v[16:19]
	v_and_b32_e32 v63, 0xffff0000, v63
	v_mfma_f32_4x4x1_16b_f32 v[4:7], v22, v120, v[4:7]
	v_mfma_f32_4x4x1_16b_f32 v[8:11], v22, v128, v[8:11]
	v_lshlrev_b32_e32 v32, 16, v64
	v_mfma_f32_4x4x1_16b_f32 v[12:15], v26, v120, v[12:15]
	v_mfma_f32_4x4x1_16b_f32 v[16:19], v26, v128, v[16:19]
	v_and_b32_e32 v64, 0xffff0000, v64
	v_mfma_f32_4x4x1_16b_f32 v[4:7], v54, v121, v[4:7]
	v_mfma_f32_4x4x1_16b_f32 v[8:11], v54, v129, v[8:11]
	v_lshlrev_b32_e32 v33, 16, v65
	v_mfma_f32_4x4x1_16b_f32 v[12:15], v58, v121, v[12:15]
	v_mfma_f32_4x4x1_16b_f32 v[16:19], v58, v129, v[16:19]
	v_and_b32_e32 v65, 0xffff0000, v65
	v_mfma_f32_4x4x1_16b_f32 v[4:7], v23, v122, v[4:7]
	v_mfma_f32_4x4x1_16b_f32 v[8:11], v23, v130, v[8:11]
	v_lshlrev_b32_e32 v34, 16, v66
	v_mfma_f32_4x4x1_16b_f32 v[12:15], v27, v122, v[12:15]
	v_mfma_f32_4x4x1_16b_f32 v[16:19], v27, v130, v[16:19]
	v_and_b32_e32 v66, 0xffff0000, v66
	v_mfma_f32_4x4x1_16b_f32 v[4:7], v55, v123, v[4:7]
	v_mfma_f32_4x4x1_16b_f32 v[8:11], v55, v131, v[8:11]
	v_lshlrev_b32_e32 v35, 16, v67
	v_mfma_f32_4x4x1_16b_f32 v[12:15], v59, v123, v[12:15]
	v_mfma_f32_4x4x1_16b_f32 v[16:19], v59, v131, v[16:19]
	v_and_b32_e32 v67, 0xffff0000, v67
	s_add_i32 s1, s13, 8
	s_and_b32 s1, s1, 15
	s_lshl_b32 s1, s1, 8
	s_add_u32 s10, s6, s1
	s_addc_u32 s11, s7, 0
	global_load_dwordx4 v[52:55], v2, s[10:11]
	global_load_dwordx4 v[56:59], v132, s[10:11]
	s_add_i32 s1, s13, 5
	s_and_b32 s1, s1, 15
	s_lshl_b32 s1, s1, 12
	s_add_u32 s36, s8, s1
	s_addc_u32 s37, s9, 0
	global_load_dwordx4 v[116:119], v3, s[36:37] offset:0
	global_load_dwordx4 v[120:123], v3, s[36:37] offset:1024
	global_load_dwordx4 v[124:127], v3, s[36:37] offset:2048
	global_load_dwordx4 v[128:131], v3, s[36:37] offset:3072
	s_waitcnt vmcnt(12)
; __global__ void __launch_bounds__(NWAVES * 64, 2) fwd_megakernel(Args args) {
;     ...
;                     for (int jj = 0; jj < 4; ++jj) pw[q][jj] = *(const u32x4*)(XB + (size_t)(m0 + q) * DM + 512 * jj + 8 * ln); }
; #pragma unroll
;                 for (int q = 0; q < 4; ++q) { float d = 0.f;
; #pragma unroll
;                     for (int jj = 0; jj < 4; ++jj) { const u32x4 w = pw[q][jj];
;                         d += __uint_as_float(w.x << 16) * wreg[8 * jj + 0] + __uint_as_float(w.x & 0xffff0000u) * wreg[8 * jj + 1] + __uint_as_float(w.y << 16) * wreg[8 * jj + 2] + __uint_as_float(w.y & 0xffff0000u) * wreg[8 * jj + 3]
;                            + __uint_as_float(w.z << 16) * wreg[8 * jj + 4] + __uint_as_float(w.z & 0xffff0000u) * wreg[8 * jj + 5] + __uint_as_float(w.w << 16) * wreg[8 * jj + 6] + __uint_as_float(w.w & 0xffff0000u) * wreg[8 * jj + 7]; }
	v_mfma_f32_4x4x1_16b_f32 v[4:7], v28, v84, v[4:7]
	v_mfma_f32_4x4x1_16b_f32 v[8:11], v28, v92, v[8:11]
	v_lshlrev_b32_e32 v20, 16, v68
	v_mfma_f32_4x4x1_16b_f32 v[12:15], v32, v84, v[12:15]
	v_mfma_f32_4x4x1_16b_f32 v[16:19], v32, v92, v[16:19]
	v_and_b32_e32 v68, 0xffff0000, v68
	v_mfma_f32_4x4x1_16b_f32 v[4:7], v60, v85, v[4:7]
	v_mfma_f32_4x4x1_16b_f32 v[8:11], v60, v93, v[8:11]
	v_lshlrev_b32_e32 v21, 16, v69
	v_mfma_f32_4x4x1_16b_f32 v[12:15], v64, v85, v[12:15]
	v_mfma_f32_4x4x1_16b_f32 v[16:19], v64, v93, v[16:19]
	v_and_b32_e32 v69, 0xffff0000, v69
	v_mfma_f32_4x4x1_16b_f32 v[4:7], v29, v86, v[4:7]
	v_mfma_f32_4x4x1_16b_f32 v[8:11], v29, v94, v[8:11]
	v_lshlrev_b32_e32 v22, 16, v70
	v_mfma_f32_4x4x1_16b_f32 v[12:15], v33, v86, v[12:15]
	v_mfma_f32_4x4x1_16b_f32 v[16:19], v33, v94, v[16:19]
	v_and_b32_e32 v70, 0xffff0000, v70
	v_mfma_f32_4x4x1_16b_f32 v[4:7], v61, v87, v[4:7]
	v_mfma_f32_4x4x1_16b_f32 v[8:11], v61, v95, v[8:11]
	v_lshlrev_b32_e32 v23, 16, v71
	v_mfma_f32_4x4x1_16b_f32 v[12:15], v65, v87, v[12:15]
	v_mfma_f32_4x4x1_16b_f32 v[16:19], v65, v95, v[16:19]
	v_and_b32_e32 v71, 0xffff0000, v71
	v_mfma_f32_4x4x1_16b_f32 v[4:7], v30, v88, v[4:7]
	v_mfma_f32_4x4x1_16b_f32 v[8:11], v30, v96, v[8:11]
	v_lshlrev_b32_e32 v24, 16, v72
	v_mfma_f32_4x4x1_16b_f32 v[12:15], v34, v88, v[12:15]
	v_mfma_f32_4x4x1_16b_f32 v[16:19], v34, v96, v[16:19]
	v_and_b32_e32 v72, 0xffff0000, v72
	v_mfma_f32_4x4x1_16b_f32 v[4:7], v62, v89, v[4:7]
	v_mfma_f32_4x4x1_16b_f32 v[8:11], v62, v97, v[8:11]
	v_lshlrev_b32_e32 v25, 16, v73
	v_mfma_f32_4x4x1_16b_f32 v[12:15], v66, v89, v[12:15]
	v_mfma_f32_4x4x1_16b_f32 v[16:19], v66, v97, v[16:19]
	v_and_b32_e32 v73, 0xffff0000, v73
	v_mfma_f32_4x4x1_16b_f32 v[4:7], v31, v90, v[4:7]
	v_mfma_f32_4x4x1_16b_f32 v[8:11], v31, v98, v[8:11]
	v_lshlrev_b32_e32 v26, 16, v74
	v_mfma_f32_4x4x1_16b_f32 v[12:15], v35, v90, v[12:15]
	v_mfma_f32_4x4x1_16b_f32 v[16:19], v35, v98, v[16:19]
	v_and_b32_e32 v74, 0xffff0000, v74
	v_mfma_f32_4x4x1_16b_f32 v[4:7], v63, v91, v[4:7]
	v_mfma_f32_4x4x1_16b_f32 v[8:11], v63, v99, v[8:11]
	v_lshlrev_b32_e32 v27, 16, v75
	v_mfma_f32_4x4x1_16b_f32 v[12:15], v67, v91, v[12:15]
	v_mfma_f32_4x4x1_16b_f32 v[16:19], v67, v99, v[16:19]
	v_and_b32_e32 v75, 0xffff0000, v75
	s_add_i32 s1, s13, 9
	s_and_b32 s1, s1, 15
	s_lshl_b32 s1, s1, 8
	s_add_u32 s10, s6, s1
	s_addc_u32 s11, s7, 0
	global_load_dwordx4 v[60:63], v2, s[10:11]
	global_load_dwordx4 v[64:67], v132, s[10:11]
	s_add_i32 s1, s13, 6
	s_and_b32 s1, s1, 15
	s_lshl_b32 s1, s1, 12
	s_add_u32 s36, s8, s1
	s_addc_u32 s37, s9, 0
	global_load_dwordx4 v[84:87], v3, s[36:37] offset:0
	global_load_dwordx4 v[88:91], v3, s[36:37] offset:1024
	global_load_dwordx4 v[92:95], v3, s[36:37] offset:2048
	global_load_dwordx4 v[96:99], v3, s[36:37] offset:3072
	s_waitcnt vmcnt(12)
	v_mfma_f32_4x4x1_16b_f32 v[4:7], v20, v100, v[4:7]
	v_mfma_f32_4x4x1_16b_f32 v[8:11], v20, v108, v[8:11]
	v_lshlrev_b32_e32 v28, 16, v76
	v_mfma_f32_4x4x1_16b_f32 v[12:15], v24, v100, v[12:15]
	v_mfma_f32_4x4x1_16b_f32 v[16:19], v24, v108, v[16:19]
	v_and_b32_e32 v76, 0xffff0000, v76
	v_mfma_f32_4x4x1_16b_f32 v[4:7], v68, v101, v[4:7]
	v_mfma_f32_4x4x1_16b_f32 v[8:11], v68, v109, v[8:11]
	v_lshlrev_b32_e32 v29, 16, v77
	v_mfma_f32_4x4x1_16b_f32 v[12:15], v72, v101, v[12:15]
	v_mfma_f32_4x4x1_16b_f32 v[16:19], v72, v109, v[16:19]
	v_and_b32_e32 v77, 0xffff0000, v77
	v_mfma_f32_4x4x1_16b_f32 v[4:7], v21, v102, v[4:7]
	v_mfma_f32_4x4x1_16b_f32 v[8:11], v21, v110, v[8:11]
	v_lshlrev_b32_e32 v30, 16, v78
	v_mfma_f32_4x4x1_16b_f32 v[12:15], v25, v102, v[12:15]
	v_mfma_f32_4x4x1_16b_f32 v[16:19], v25, v110, v[16:19]
	v_and_b32_e32 v78, 0xffff0000, v78
	v_mfma_f32_4x4x1_16b_f32 v[4:7], v69, v103, v[4:7]
	v_mfma_f32_4x4x1_16b_f32 v[8:11], v69, v111, v[8:11]
	v_lshlrev_b32_e32 v31, 16, v79
	v_mfma_f32_4x4x1_16b_f32 v[12:15], v73, v103, v[12:15]
	v_mfma_f32_4x4x1_16b_f32 v[16:19], v73, v111, v[16:19]
	v_and_b32_e32 v79, 0xffff0000, v79
	v_mfma_f32_4x4x1_16b_f32 v[4:7], v22, v104, v[4:7]
	v_mfma_f32_4x4x1_16b_f32 v[8:11], v22, v112, v[8:11]
	v_lshlrev_b32_e32 v32, 16, v80
	v_mfma_f32_4x4x1_16b_f32 v[12:15], v26, v104, v[12:15]
	v_mfma_f32_4x4x1_16b_f32 v[16:19], v26, v112, v[16:19]
	v_and_b32_e32 v80, 0xffff0000, v80
	v_mfma_f32_4x4x1_16b_f32 v[4:7], v70, v105, v[4:7]
	v_mfma_f32_4x4x1_16b_f32 v[8:11], v70, v113, v[8:11]
	v_lshlrev_b32_e32 v33, 16, v81
	v_mfma_f32_4x4x1_16b_f32 v[12:15], v74, v105, v[12:15]
	v_mfma_f32_4x4x1_16b_f32 v[16:19], v74, v113, v[16:19]
	v_and_b32_e32 v81, 0xffff0000, v81
	v_mfma_f32_4x4x1_16b_f32 v[4:7], v23, v106, v[4:7]
	v_mfma_f32_4x4x1_16b_f32 v[8:11], v23, v114, v[8:11]
	v_lshlrev_b32_e32 v34, 16, v82
	v_mfma_f32_4x4x1_16b_f32 v[12:15], v27, v106, v[12:15]
	v_mfma_f32_4x4x1_16b_f32 v[16:19], v27, v114, v[16:19]
	v_and_b32_e32 v82, 0xffff0000, v82
	v_mfma_f32_4x4x1_16b_f32 v[4:7], v71, v107, v[4:7]
	v_mfma_f32_4x4x1_16b_f32 v[8:11], v71, v115, v[8:11]
	v_lshlrev_b32_e32 v35, 16, v83
	v_mfma_f32_4x4x1_16b_f32 v[12:15], v75, v107, v[12:15]
	v_mfma_f32_4x4x1_16b_f32 v[16:19], v75, v115, v[16:19]
	v_and_b32_e32 v83, 0xffff0000, v83
	s_add_i32 s1, s13, 10
	s_and_b32 s1, s1, 15
	s_lshl_b32 s1, s1, 8
	s_add_u32 s10, s6, s1
	s_addc_u32 s11, s7, 0
	global_load_dwordx4 v[68:71], v2, s[10:11]
	global_load_dwordx4 v[72:75], v132, s[10:11]
	s_add_i32 s1, s13, 7
	s_and_b32 s1, s1, 15
	s_lshl_b32 s1, s1, 12
	s_add_u32 s36, s8, s1
	s_addc_u32 s37, s9, 0
	global_load_dwordx4 v[100:103], v3, s[36:37] offset:0
	global_load_dwordx4 v[104:107], v3, s[36:37] offset:1024
	global_load_dwordx4 v[108:111], v3, s[36:37] offset:2048
	global_load_dwordx4 v[112:115], v3, s[36:37] offset:3072
	s_waitcnt vmcnt(12)
; __global__ void __launch_bounds__(NWAVES * 64, 2) fwd_megakernel(Args args) {
;     ...
;                     for (int jj = 0; jj < 4; ++jj) pw[q][jj] = *(const u32x4*)(XB + (size_t)(m0 + q) * DM + 512 * jj + 8 * ln); }
; #pragma unroll
;                 for (int q = 0; q < 4; ++q) { float d = 0.f;
; #pragma unroll
;                     for (int jj = 0; jj < 4; ++jj) { const u32x4 w = pw[q][jj];
;                         d += __uint_as_float(w.x << 16) * wreg[8 * jj + 0] + __uint_as_float(w.x & 0xffff0000u) * wreg[8 * jj + 1] + __uint_as_float(w.y << 16) * wreg[8 * jj + 2] + __uint_as_float(w.y & 0xffff0000u) * wreg[8 * jj + 3]
;                            + __uint_as_float(w.z << 16) * wreg[8 * jj + 4] + __uint_as_float(w.z & 0xffff0000u) * wreg[8 * jj + 5] + __uint_as_float(w.w << 16) * wreg[8 * jj + 6] + __uint_as_float(w.w & 0xffff0000u) * wreg[8 * jj + 7]; }
	v_mfma_f32_4x4x1_16b_f32 v[4:7], v28, v116, v[4:7]
	v_mfma_f32_4x4x1_16b_f32 v[8:11], v28, v124, v[8:11]
	v_lshlrev_b32_e32 v20, 16, v36
	v_mfma_f32_4x4x1_16b_f32 v[12:15], v32, v116, v[12:15]
	v_mfma_f32_4x4x1_16b_f32 v[16:19], v32, v124, v[16:19]
	v_and_b32_e32 v36, 0xffff0000, v36
	v_mfma_f32_4x4x1_16b_f32 v[4:7], v76, v117, v[4:7]
	v_mfma_f32_4x4x1_16b_f32 v[8:11], v76, v125, v[8:11]
	v_lshlrev_b32_e32 v21, 16, v37
	v_mfma_f32_4x4x1_16b_f32 v[12:15], v80, v117, v[12:15]
	v_mfma_f32_4x4x1_16b_f32 v[16:19], v80, v125, v[16:19]
	v_and_b32_e32 v37, 0xffff0000, v37
	v_mfma_f32_4x4x1_16b_f32 v[4:7], v29, v118, v[4:7]
	v_mfma_f32_4x4x1_16b_f32 v[8:11], v29, v126, v[8:11]
	v_lshlrev_b32_e32 v22, 16, v38
	v_mfma_f32_4x4x1_16b_f32 v[12:15], v33, v118, v[12:15]
	v_mfma_f32_4x4x1_16b_f32 v[16:19], v33, v126, v[16:19]
	v_and_b32_e32 v38, 0xffff0000, v38
	v_mfma_f32_4x4x1_16b_f32 v[4:7], v77, v119, v[4:7]
	v_mfma_f32_4x4x1_16b_f32 v[8:11], v77, v127, v[8:11]
	v_lshlrev_b32_e32 v23, 16, v39
	v_mfma_f32_4x4x1_16b_f32 v[12:15], v81, v119, v[12:15]
	v_mfma_f32_4x4x1_16b_f32 v[16:19], v81, v127, v[16:19]
	v_and_b32_e32 v39, 0xffff0000, v39
	v_mfma_f32_4x4x1_16b_f32 v[4:7], v30, v120, v[4:7]
	v_mfma_f32_4x4x1_16b_f32 v[8:11], v30, v128, v[8:11]
	v_lshlrev_b32_e32 v24, 16, v40
	v_mfma_f32_4x4x1_16b_f32 v[12:15], v34, v120, v[12:15]
	v_mfma_f32_4x4x1_16b_f32 v[16:19], v34, v128, v[16:19]
	v_and_b32_e32 v40, 0xffff0000, v40
	v_mfma_f32_4x4x1_16b_f32 v[4:7], v78, v121, v[4:7]
	v_mfma_f32_4x4x1_16b_f32 v[8:11], v78, v129, v[8:11]
	v_lshlrev_b32_e32 v25, 16, v41
	v_mfma_f32_4x4x1_16b_f32 v[12:15], v82, v121, v[12:15]
	v_mfma_f32_4x4x1_16b_f32 v[16:19], v82, v129, v[16:19]
	v_and_b32_e32 v41, 0xffff0000, v41
	v_mfma_f32_4x4x1_16b_f32 v[4:7], v31, v122, v[4:7]
	v_mfma_f32_4x4x1_16b_f32 v[8:11], v31, v130, v[8:11]
	v_lshlrev_b32_e32 v26, 16, v42
	v_mfma_f32_4x4x1_16b_f32 v[12:15], v35, v122, v[12:15]
	v_mfma_f32_4x4x1_16b_f32 v[16:19], v35, v130, v[16:19]
	v_and_b32_e32 v42, 0xffff0000, v42
	v_mfma_f32_4x4x1_16b_f32 v[4:7], v79, v123, v[4:7]
	v_mfma_f32_4x4x1_16b_f32 v[8:11], v79, v131, v[8:11]
	v_lshlrev_b32_e32 v27, 16, v43
	v_mfma_f32_4x4x1_16b_f32 v[12:15], v83, v123, v[12:15]
	v_mfma_f32_4x4x1_16b_f32 v[16:19], v83, v131, v[16:19]
	v_and_b32_e32 v43, 0xffff0000, v43
	s_add_i32 s1, s13, 11
	s_and_b32 s1, s1, 15
	s_lshl_b32 s1, s1, 8
	s_add_u32 s10, s6, s1
	s_addc_u32 s11, s7, 0
	global_load_dwordx4 v[76:79], v2, s[10:11]
	global_load_dwordx4 v[80:83], v132, s[10:11]
	s_add_i32 s1, s13, 8
	s_and_b32 s1, s1, 15
	s_lshl_b32 s1, s1, 12
	s_add_u32 s36, s8, s1
	s_addc_u32 s37, s9, 0
	global_load_dwordx4 v[116:119], v3, s[36:37] offset:0
	global_load_dwordx4 v[120:123], v3, s[36:37] offset:1024
	global_load_dwordx4 v[124:127], v3, s[36:37] offset:2048
	global_load_dwordx4 v[128:131], v3, s[36:37] offset:3072
	s_waitcnt vmcnt(12)
	v_mfma_f32_4x4x1_16b_f32 v[4:7], v20, v84, v[4:7]
	v_mfma_f32_4x4x1_16b_f32 v[8:11], v20, v92, v[8:11]
	v_lshlrev_b32_e32 v28, 16, v44
	v_mfma_f32_4x4x1_16b_f32 v[12:15], v24, v84, v[12:15]
	v_mfma_f32_4x4x1_16b_f32 v[16:19], v24, v92, v[16:19]
	v_and_b32_e32 v44, 0xffff0000, v44
	v_mfma_f32_4x4x1_16b_f32 v[4:7], v36, v85, v[4:7]
	v_mfma_f32_4x4x1_16b_f32 v[8:11], v36, v93, v[8:11]
	v_lshlrev_b32_e32 v29, 16, v45
	v_mfma_f32_4x4x1_16b_f32 v[12:15], v40, v85, v[12:15]
	v_mfma_f32_4x4x1_16b_f32 v[16:19], v40, v93, v[16:19]
	v_and_b32_e32 v45, 0xffff0000, v45
	v_mfma_f32_4x4x1_16b_f32 v[4:7], v21, v86, v[4:7]
	v_mfma_f32_4x4x1_16b_f32 v[8:11], v21, v94, v[8:11]
	v_lshlrev_b32_e32 v30, 16, v46
	v_mfma_f32_4x4x1_16b_f32 v[12:15], v25, v86, v[12:15]
	v_mfma_f32_4x4x1_16b_f32 v[16:19], v25, v94, v[16:19]
	v_and_b32_e32 v46, 0xffff0000, v46
	v_mfma_f32_4x4x1_16b_f32 v[4:7], v37, v87, v[4:7]
	v_mfma_f32_4x4x1_16b_f32 v[8:11], v37, v95, v[8:11]
	v_lshlrev_b32_e32 v31, 16, v47
	v_mfma_f32_4x4x1_16b_f32 v[12:15], v41, v87, v[12:15]
	v_mfma_f32_4x4x1_16b_f32 v[16:19], v41, v95, v[16:19]
	v_and_b32_e32 v47, 0xffff0000, v47
	v_mfma_f32_4x4x1_16b_f32 v[4:7], v22, v88, v[4:7]
	v_mfma_f32_4x4x1_16b_f32 v[8:11], v22, v96, v[8:11]
	v_lshlrev_b32_e32 v32, 16, v48
	v_mfma_f32_4x4x1_16b_f32 v[12:15], v26, v88, v[12:15]
	v_mfma_f32_4x4x1_16b_f32 v[16:19], v26, v96, v[16:19]
	v_and_b32_e32 v48, 0xffff0000, v48
	v_mfma_f32_4x4x1_16b_f32 v[4:7], v38, v89, v[4:7]
	v_mfma_f32_4x4x1_16b_f32 v[8:11], v38, v97, v[8:11]
	v_lshlrev_b32_e32 v33, 16, v49
	v_mfma_f32_4x4x1_16b_f32 v[12:15], v42, v89, v[12:15]
	v_mfma_f32_4x4x1_16b_f32 v[16:19], v42, v97, v[16:19]
	v_and_b32_e32 v49, 0xffff0000, v49
	v_mfma_f32_4x4x1_16b_f32 v[4:7], v23, v90, v[4:7]
	v_mfma_f32_4x4x1_16b_f32 v[8:11], v23, v98, v[8:11]
	v_lshlrev_b32_e32 v34, 16, v50
	v_mfma_f32_4x4x1_16b_f32 v[12:15], v27, v90, v[12:15]
	v_mfma_f32_4x4x1_16b_f32 v[16:19], v27, v98, v[16:19]
	v_and_b32_e32 v50, 0xffff0000, v50
	v_mfma_f32_4x4x1_16b_f32 v[4:7], v39, v91, v[4:7]
	v_mfma_f32_4x4x1_16b_f32 v[8:11], v39, v99, v[8:11]
	v_lshlrev_b32_e32 v35, 16, v51
	v_mfma_f32_4x4x1_16b_f32 v[12:15], v43, v91, v[12:15]
	v_mfma_f32_4x4x1_16b_f32 v[16:19], v43, v99, v[16:19]
	v_and_b32_e32 v51, 0xffff0000, v51
	s_add_i32 s1, s13, 12
	s_and_b32 s1, s1, 15
	s_lshl_b32 s1, s1, 8
	s_add_u32 s10, s6, s1
	s_addc_u32 s11, s7, 0
	global_load_dwordx4 v[36:39], v2, s[10:11]
	global_load_dwordx4 v[40:43], v132, s[10:11]
	s_add_i32 s1, s13, 9
	s_and_b32 s1, s1, 15
	s_lshl_b32 s1, s1, 12
	s_add_u32 s36, s8, s1
	s_addc_u32 s37, s9, 0
	global_load_dwordx4 v[84:87], v3, s[36:37] offset:0
	global_load_dwordx4 v[88:91], v3, s[36:37] offset:1024
	global_load_dwordx4 v[92:95], v3, s[36:37] offset:2048
	global_load_dwordx4 v[96:99], v3, s[36:37] offset:3072
	s_waitcnt vmcnt(12)
; __global__ void __launch_bounds__(NWAVES * 64, 2) fwd_megakernel(Args args) {
;     ...
;                     for (int jj = 0; jj < 4; ++jj) pw[q][jj] = *(const u32x4*)(XB + (size_t)(m0 + q) * DM + 512 * jj + 8 * ln); }
; #pragma unroll
;                 for (int q = 0; q < 4; ++q) { float d = 0.f;
; #pragma unroll
;                     for (int jj = 0; jj < 4; ++jj) { const u32x4 w = pw[q][jj];
;                         d += __uint_as_float(w.x << 16) * wreg[8 * jj + 0] + __uint_as_float(w.x & 0xffff0000u) * wreg[8 * jj + 1] + __uint_as_float(w.y << 16) * wreg[8 * jj + 2] + __uint_as_float(w.y & 0xffff0000u) * wreg[8 * jj + 3]
;                            + __uint_as_float(w.z << 16) * wreg[8 * jj + 4] + __uint_as_float(w.z & 0xffff0000u) * wreg[8 * jj + 5] + __uint_as_float(w.w << 16) * wreg[8 * jj + 6] + __uint_as_float(w.w & 0xffff0000u) * wreg[8 * jj + 7]; }
	v_mfma_f32_4x4x1_16b_f32 v[4:7], v28, v100, v[4:7]
	v_mfma_f32_4x4x1_16b_f32 v[8:11], v28, v108, v[8:11]
	v_lshlrev_b32_e32 v20, 16, v52
	v_mfma_f32_4x4x1_16b_f32 v[12:15], v32, v100, v[12:15]
	v_mfma_f32_4x4x1_16b_f32 v[16:19], v32, v108, v[16:19]
	v_and_b32_e32 v52, 0xffff0000, v52
	v_mfma_f32_4x4x1_16b_f32 v[4:7], v44, v101, v[4:7]
	v_mfma_f32_4x4x1_16b_f32 v[8:11], v44, v109, v[8:11]
	v_lshlrev_b32_e32 v21, 16, v53
	v_mfma_f32_4x4x1_16b_f32 v[12:15], v48, v101, v[12:15]
	v_mfma_f32_4x4x1_16b_f32 v[16:19], v48, v109, v[16:19]
	v_and_b32_e32 v53, 0xffff0000, v53
	v_mfma_f32_4x4x1_16b_f32 v[4:7], v29, v102, v[4:7]
	v_mfma_f32_4x4x1_16b_f32 v[8:11], v29, v110, v[8:11]
	v_lshlrev_b32_e32 v22, 16, v54
	v_mfma_f32_4x4x1_16b_f32 v[12:15], v33, v102, v[12:15]
	v_mfma_f32_4x4x1_16b_f32 v[16:19], v33, v110, v[16:19]
	v_and_b32_e32 v54, 0xffff0000, v54
	v_mfma_f32_4x4x1_16b_f32 v[4:7], v45, v103, v[4:7]
	v_mfma_f32_4x4x1_16b_f32 v[8:11], v45, v111, v[8:11]
	v_lshlrev_b32_e32 v23, 16, v55
	v_mfma_f32_4x4x1_16b_f32 v[12:15], v49, v103, v[12:15]
	v_mfma_f32_4x4x1_16b_f32 v[16:19], v49, v111, v[16:19]
	v_and_b32_e32 v55, 0xffff0000, v55
	v_mfma_f32_4x4x1_16b_f32 v[4:7], v30, v104, v[4:7]
	v_mfma_f32_4x4x1_16b_f32 v[8:11], v30, v112, v[8:11]
	v_lshlrev_b32_e32 v24, 16, v56
	v_mfma_f32_4x4x1_16b_f32 v[12:15], v34, v104, v[12:15]
	v_mfma_f32_4x4x1_16b_f32 v[16:19], v34, v112, v[16:19]
	v_and_b32_e32 v56, 0xffff0000, v56
	v_mfma_f32_4x4x1_16b_f32 v[4:7], v46, v105, v[4:7]
	v_mfma_f32_4x4x1_16b_f32 v[8:11], v46, v113, v[8:11]
	v_lshlrev_b32_e32 v25, 16, v57
	v_mfma_f32_4x4x1_16b_f32 v[12:15], v50, v105, v[12:15]
	v_mfma_f32_4x4x1_16b_f32 v[16:19], v50, v113, v[16:19]
	v_and_b32_e32 v57, 0xffff0000, v57
	v_mfma_f32_4x4x1_16b_f32 v[4:7], v31, v106, v[4:7]
	v_mfma_f32_4x4x1_16b_f32 v[8:11], v31, v114, v[8:11]
	v_lshlrev_b32_e32 v26, 16, v58
	v_mfma_f32_4x4x1_16b_f32 v[12:15], v35, v106, v[12:15]
	v_mfma_f32_4x4x1_16b_f32 v[16:19], v35, v114, v[16:19]
	v_and_b32_e32 v58, 0xffff0000, v58
	v_mfma_f32_4x4x1_16b_f32 v[4:7], v47, v107, v[4:7]
	v_mfma_f32_4x4x1_16b_f32 v[8:11], v47, v115, v[8:11]
	v_lshlrev_b32_e32 v27, 16, v59
	v_mfma_f32_4x4x1_16b_f32 v[12:15], v51, v107, v[12:15]
	v_mfma_f32_4x4x1_16b_f32 v[16:19], v51, v115, v[16:19]
	v_and_b32_e32 v59, 0xffff0000, v59
	s_add_i32 s1, s13, 13
	s_and_b32 s1, s1, 15
	s_lshl_b32 s1, s1, 8
	s_add_u32 s10, s6, s1
	s_addc_u32 s11, s7, 0
	global_load_dwordx4 v[44:47], v2, s[10:11]
	global_load_dwordx4 v[48:51], v132, s[10:11]
	s_add_i32 s1, s13, 10
	s_and_b32 s1, s1, 15
	s_lshl_b32 s1, s1, 12
	s_add_u32 s36, s8, s1
	s_addc_u32 s37, s9, 0
	global_load_dwordx4 v[100:103], v3, s[36:37] offset:0
	global_load_dwordx4 v[104:107], v3, s[36:37] offset:1024
	global_load_dwordx4 v[108:111], v3, s[36:37] offset:2048
	global_load_dwordx4 v[112:115], v3, s[36:37] offset:3072
	s_waitcnt vmcnt(12)
	v_mfma_f32_4x4x1_16b_f32 v[4:7], v20, v116, v[4:7]
	v_mfma_f32_4x4x1_16b_f32 v[8:11], v20, v124, v[8:11]
	v_lshlrev_b32_e32 v28, 16, v60
	v_mfma_f32_4x4x1_16b_f32 v[12:15], v24, v116, v[12:15]
	v_mfma_f32_4x4x1_16b_f32 v[16:19], v24, v124, v[16:19]
	v_and_b32_e32 v60, 0xffff0000, v60
	v_mfma_f32_4x4x1_16b_f32 v[4:7], v52, v117, v[4:7]
	v_mfma_f32_4x4x1_16b_f32 v[8:11], v52, v125, v[8:11]
	v_lshlrev_b32_e32 v29, 16, v61
	v_mfma_f32_4x4x1_16b_f32 v[12:15], v56, v117, v[12:15]
	v_mfma_f32_4x4x1_16b_f32 v[16:19], v56, v125, v[16:19]
	v_and_b32_e32 v61, 0xffff0000, v61
	v_mfma_f32_4x4x1_16b_f32 v[4:7], v21, v118, v[4:7]
	v_mfma_f32_4x4x1_16b_f32 v[8:11], v21, v126, v[8:11]
	v_lshlrev_b32_e32 v30, 16, v62
	v_mfma_f32_4x4x1_16b_f32 v[12:15], v25, v118, v[12:15]
	v_mfma_f32_4x4x1_16b_f32 v[16:19], v25, v126, v[16:19]
	v_and_b32_e32 v62, 0xffff0000, v62
	v_mfma_f32_4x4x1_16b_f32 v[4:7], v53, v119, v[4:7]
	v_mfma_f32_4x4x1_16b_f32 v[8:11], v53, v127, v[8:11]
	v_lshlrev_b32_e32 v31, 16, v63
	v_mfma_f32_4x4x1_16b_f32 v[12:15], v57, v119, v[12:15]
	v_mfma_f32_4x4x1_16b_f32 v[16:19], v57, v127, v[16:19]
	v_and_b32_e32 v63, 0xffff0000, v63
	v_mfma_f32_4x4x1_16b_f32 v[4:7], v22, v120, v[4:7]
	v_mfma_f32_4x4x1_16b_f32 v[8:11], v22, v128, v[8:11]
	v_lshlrev_b32_e32 v32, 16, v64
	v_mfma_f32_4x4x1_16b_f32 v[12:15], v26, v120, v[12:15]
	v_mfma_f32_4x4x1_16b_f32 v[16:19], v26, v128, v[16:19]
	v_and_b32_e32 v64, 0xffff0000, v64
	v_mfma_f32_4x4x1_16b_f32 v[4:7], v54, v121, v[4:7]
	v_mfma_f32_4x4x1_16b_f32 v[8:11], v54, v129, v[8:11]
	v_lshlrev_b32_e32 v33, 16, v65
	v_mfma_f32_4x4x1_16b_f32 v[12:15], v58, v121, v[12:15]
	v_mfma_f32_4x4x1_16b_f32 v[16:19], v58, v129, v[16:19]
	v_and_b32_e32 v65, 0xffff0000, v65
	v_mfma_f32_4x4x1_16b_f32 v[4:7], v23, v122, v[4:7]
	v_mfma_f32_4x4x1_16b_f32 v[8:11], v23, v130, v[8:11]
	v_lshlrev_b32_e32 v34, 16, v66
	v_mfma_f32_4x4x1_16b_f32 v[12:15], v27, v122, v[12:15]
	v_mfma_f32_4x4x1_16b_f32 v[16:19], v27, v130, v[16:19]
	v_and_b32_e32 v66, 0xffff0000, v66
	v_mfma_f32_4x4x1_16b_f32 v[4:7], v55, v123, v[4:7]
	v_mfma_f32_4x4x1_16b_f32 v[8:11], v55, v131, v[8:11]
	v_lshlrev_b32_e32 v35, 16, v67
	v_mfma_f32_4x4x1_16b_f32 v[12:15], v59, v123, v[12:15]
	v_mfma_f32_4x4x1_16b_f32 v[16:19], v59, v131, v[16:19]
	v_and_b32_e32 v67, 0xffff0000, v67
	s_add_i32 s1, s13, 14
	s_and_b32 s1, s1, 15
	s_lshl_b32 s1, s1, 8
	s_add_u32 s10, s6, s1
	s_addc_u32 s11, s7, 0
	global_load_dwordx4 v[52:55], v2, s[10:11]
	global_load_dwordx4 v[56:59], v132, s[10:11]
	s_add_i32 s1, s13, 11
	s_and_b32 s1, s1, 15
	s_lshl_b32 s1, s1, 12
	s_add_u32 s36, s8, s1
	s_addc_u32 s37, s9, 0
	global_load_dwordx4 v[116:119], v3, s[36:37] offset:0
	global_load_dwordx4 v[120:123], v3, s[36:37] offset:1024
	global_load_dwordx4 v[124:127], v3, s[36:37] offset:2048
	global_load_dwordx4 v[128:131], v3, s[36:37] offset:3072
	s_waitcnt vmcnt(12)
; __global__ void __launch_bounds__(NWAVES * 64, 2) fwd_megakernel(Args args) {
;     ...
;                     for (int jj = 0; jj < 4; ++jj) pw[q][jj] = *(const u32x4*)(XB + (size_t)(m0 + q) * DM + 512 * jj + 8 * ln); }
; #pragma unroll
;                 for (int q = 0; q < 4; ++q) { float d = 0.f;
; #pragma unroll
;                     for (int jj = 0; jj < 4; ++jj) { const u32x4 w = pw[q][jj];
;                         d += __uint_as_float(w.x << 16) * wreg[8 * jj + 0] + __uint_as_float(w.x & 0xffff0000u) * wreg[8 * jj + 1] + __uint_as_float(w.y << 16) * wreg[8 * jj + 2] + __uint_as_float(w.y & 0xffff0000u) * wreg[8 * jj + 3]
;                            + __uint_as_float(w.z << 16) * wreg[8 * jj + 4] + __uint_as_float(w.z & 0xffff0000u) * wreg[8 * jj + 5] + __uint_as_float(w.w << 16) * wreg[8 * jj + 6] + __uint_as_float(w.w & 0xffff0000u) * wreg[8 * jj + 7]; }
	v_mfma_f32_4x4x1_16b_f32 v[4:7], v28, v84, v[4:7]
	v_mfma_f32_4x4x1_16b_f32 v[8:11], v28, v92, v[8:11]
	v_lshlrev_b32_e32 v20, 16, v68
	v_mfma_f32_4x4x1_16b_f32 v[12:15], v32, v84, v[12:15]
	v_mfma_f32_4x4x1_16b_f32 v[16:19], v32, v92, v[16:19]
	v_and_b32_e32 v68, 0xffff0000, v68
	v_mfma_f32_4x4x1_16b_f32 v[4:7], v60, v85, v[4:7]
	v_mfma_f32_4x4x1_16b_f32 v[8:11], v60, v93, v[8:11]
	v_lshlrev_b32_e32 v21, 16, v69
	v_mfma_f32_4x4x1_16b_f32 v[12:15], v64, v85, v[12:15]
	v_mfma_f32_4x4x1_16b_f32 v[16:19], v64, v93, v[16:19]
	v_and_b32_e32 v69, 0xffff0000, v69
	v_mfma_f32_4x4x1_16b_f32 v[4:7], v29, v86, v[4:7]
	v_mfma_f32_4x4x1_16b_f32 v[8:11], v29, v94, v[8:11]
	v_lshlrev_b32_e32 v22, 16, v70
	v_mfma_f32_4x4x1_16b_f32 v[12:15], v33, v86, v[12:15]
	v_mfma_f32_4x4x1_16b_f32 v[16:19], v33, v94, v[16:19]
	v_and_b32_e32 v70, 0xffff0000, v70
	v_mfma_f32_4x4x1_16b_f32 v[4:7], v61, v87, v[4:7]
	v_mfma_f32_4x4x1_16b_f32 v[8:11], v61, v95, v[8:11]
	v_lshlrev_b32_e32 v23, 16, v71
	v_mfma_f32_4x4x1_16b_f32 v[12:15], v65, v87, v[12:15]
	v_mfma_f32_4x4x1_16b_f32 v[16:19], v65, v95, v[16:19]
	v_and_b32_e32 v71, 0xffff0000, v71
	v_mfma_f32_4x4x1_16b_f32 v[4:7], v30, v88, v[4:7]
	v_mfma_f32_4x4x1_16b_f32 v[8:11], v30, v96, v[8:11]
	v_lshlrev_b32_e32 v24, 16, v72
	v_mfma_f32_4x4x1_16b_f32 v[12:15], v34, v88, v[12:15]
	v_mfma_f32_4x4x1_16b_f32 v[16:19], v34, v96, v[16:19]
	v_and_b32_e32 v72, 0xffff0000, v72
	v_mfma_f32_4x4x1_16b_f32 v[4:7], v62, v89, v[4:7]
	v_mfma_f32_4x4x1_16b_f32 v[8:11], v62, v97, v[8:11]
	v_lshlrev_b32_e32 v25, 16, v73
	v_mfma_f32_4x4x1_16b_f32 v[12:15], v66, v89, v[12:15]
	v_mfma_f32_4x4x1_16b_f32 v[16:19], v66, v97, v[16:19]
	v_and_b32_e32 v73, 0xffff0000, v73
	v_mfma_f32_4x4x1_16b_f32 v[4:7], v31, v90, v[4:7]
	v_mfma_f32_4x4x1_16b_f32 v[8:11], v31, v98, v[8:11]
	v_lshlrev_b32_e32 v26, 16, v74
	v_mfma_f32_4x4x1_16b_f32 v[12:15], v35, v90, v[12:15]
	v_mfma_f32_4x4x1_16b_f32 v[16:19], v35, v98, v[16:19]
	v_and_b32_e32 v74, 0xffff0000, v74
	v_mfma_f32_4x4x1_16b_f32 v[4:7], v63, v91, v[4:7]
	v_mfma_f32_4x4x1_16b_f32 v[8:11], v63, v99, v[8:11]
	v_lshlrev_b32_e32 v27, 16, v75
	v_mfma_f32_4x4x1_16b_f32 v[12:15], v67, v91, v[12:15]
	v_mfma_f32_4x4x1_16b_f32 v[16:19], v67, v99, v[16:19]
	v_and_b32_e32 v75, 0xffff0000, v75
	s_add_i32 s1, s13, 15
	s_and_b32 s1, s1, 15
	s_lshl_b32 s1, s1, 8
	s_add_u32 s10, s6, s1
	s_addc_u32 s11, s7, 0
	global_load_dwordx4 v[60:63], v2, s[10:11]
	global_load_dwordx4 v[64:67], v132, s[10:11]
	s_add_i32 s1, s13, 12
	s_and_b32 s1, s1, 15
	s_lshl_b32 s1, s1, 12
	s_add_u32 s36, s8, s1
	s_addc_u32 s37, s9, 0
	global_load_dwordx4 v[84:87], v3, s[36:37] offset:0
	global_load_dwordx4 v[88:91], v3, s[36:37] offset:1024
	global_load_dwordx4 v[92:95], v3, s[36:37] offset:2048
	global_load_dwordx4 v[96:99], v3, s[36:37] offset:3072
	s_waitcnt vmcnt(12)
	v_mfma_f32_4x4x1_16b_f32 v[4:7], v20, v100, v[4:7]
	v_mfma_f32_4x4x1_16b_f32 v[8:11], v20, v108, v[8:11]
	v_lshlrev_b32_e32 v28, 16, v76
	v_mfma_f32_4x4x1_16b_f32 v[12:15], v24, v100, v[12:15]
	v_mfma_f32_4x4x1_16b_f32 v[16:19], v24, v108, v[16:19]
	v_and_b32_e32 v76, 0xffff0000, v76
	v_mfma_f32_4x4x1_16b_f32 v[4:7], v68, v101, v[4:7]
	v_mfma_f32_4x4x1_16b_f32 v[8:11], v68, v109, v[8:11]
	v_lshlrev_b32_e32 v29, 16, v77
	v_mfma_f32_4x4x1_16b_f32 v[12:15], v72, v101, v[12:15]
	v_mfma_f32_4x4x1_16b_f32 v[16:19], v72, v109, v[16:19]
	v_and_b32_e32 v77, 0xffff0000, v77
	v_mfma_f32_4x4x1_16b_f32 v[4:7], v21, v102, v[4:7]
	v_mfma_f32_4x4x1_16b_f32 v[8:11], v21, v110, v[8:11]
	v_lshlrev_b32_e32 v30, 16, v78
	v_mfma_f32_4x4x1_16b_f32 v[12:15], v25, v102, v[12:15]
	v_mfma_f32_4x4x1_16b_f32 v[16:19], v25, v110, v[16:19]
	v_and_b32_e32 v78, 0xffff0000, v78
	v_mfma_f32_4x4x1_16b_f32 v[4:7], v69, v103, v[4:7]
	v_mfma_f32_4x4x1_16b_f32 v[8:11], v69, v111, v[8:11]
	v_lshlrev_b32_e32 v31, 16, v79
	v_mfma_f32_4x4x1_16b_f32 v[12:15], v73, v103, v[12:15]
	v_mfma_f32_4x4x1_16b_f32 v[16:19], v73, v111, v[16:19]
	v_and_b32_e32 v79, 0xffff0000, v79
	v_mfma_f32_4x4x1_16b_f32 v[4:7], v22, v104, v[4:7]
	v_mfma_f32_4x4x1_16b_f32 v[8:11], v22, v112, v[8:11]
	v_lshlrev_b32_e32 v32, 16, v80
	v_mfma_f32_4x4x1_16b_f32 v[12:15], v26, v104, v[12:15]
	v_mfma_f32_4x4x1_16b_f32 v[16:19], v26, v112, v[16:19]
	v_and_b32_e32 v80, 0xffff0000, v80
	v_mfma_f32_4x4x1_16b_f32 v[4:7], v70, v105, v[4:7]
	v_mfma_f32_4x4x1_16b_f32 v[8:11], v70, v113, v[8:11]
	v_lshlrev_b32_e32 v33, 16, v81
	v_mfma_f32_4x4x1_16b_f32 v[12:15], v74, v105, v[12:15]
	v_mfma_f32_4x4x1_16b_f32 v[16:19], v74, v113, v[16:19]
	v_and_b32_e32 v81, 0xffff0000, v81
	v_mfma_f32_4x4x1_16b_f32 v[4:7], v23, v106, v[4:7]
	v_mfma_f32_4x4x1_16b_f32 v[8:11], v23, v114, v[8:11]
	v_lshlrev_b32_e32 v34, 16, v82
	v_mfma_f32_4x4x1_16b_f32 v[12:15], v27, v106, v[12:15]
	v_mfma_f32_4x4x1_16b_f32 v[16:19], v27, v114, v[16:19]
	v_and_b32_e32 v82, 0xffff0000, v82
	v_mfma_f32_4x4x1_16b_f32 v[4:7], v71, v107, v[4:7]
	v_mfma_f32_4x4x1_16b_f32 v[8:11], v71, v115, v[8:11]
	v_lshlrev_b32_e32 v35, 16, v83
	v_mfma_f32_4x4x1_16b_f32 v[12:15], v75, v107, v[12:15]
	v_mfma_f32_4x4x1_16b_f32 v[16:19], v75, v115, v[16:19]
	v_and_b32_e32 v83, 0xffff0000, v83
	s_add_i32 s1, s13, 13
	s_and_b32 s1, s1, 15
	s_lshl_b32 s1, s1, 12
	s_add_u32 s36, s8, s1
	s_addc_u32 s37, s9, 0
	global_load_dwordx4 v[100:103], v3, s[36:37] offset:0
	global_load_dwordx4 v[104:107], v3, s[36:37] offset:1024
	global_load_dwordx4 v[108:111], v3, s[36:37] offset:2048
	global_load_dwordx4 v[112:115], v3, s[36:37] offset:3072
	s_waitcnt vmcnt(10)
; __global__ void __launch_bounds__(NWAVES * 64, 2) fwd_megakernel(Args args) {
;     ...
;                     for (int jj = 0; jj < 4; ++jj) pw[q][jj] = *(const u32x4*)(XB + (size_t)(m0 + q) * DM + 512 * jj + 8 * ln); }
; #pragma unroll
;                 for (int q = 0; q < 4; ++q) { float d = 0.f;
; #pragma unroll
;                     for (int jj = 0; jj < 4; ++jj) { const u32x4 w = pw[q][jj];
;                         d += __uint_as_float(w.x << 16) * wreg[8 * jj + 0] + __uint_as_float(w.x & 0xffff0000u) * wreg[8 * jj + 1] + __uint_as_float(w.y << 16) * wreg[8 * jj + 2] + __uint_as_float(w.y & 0xffff0000u) * wreg[8 * jj + 3]
;                            + __uint_as_float(w.z << 16) * wreg[8 * jj + 4] + __uint_as_float(w.z & 0xffff0000u) * wreg[8 * jj + 5] + __uint_as_float(w.w << 16) * wreg[8 * jj + 6] + __uint_as_float(w.w & 0xffff0000u) * wreg[8 * jj + 7]; }
	v_mfma_f32_4x4x1_16b_f32 v[4:7], v28, v116, v[4:7]
	v_mfma_f32_4x4x1_16b_f32 v[8:11], v28, v124, v[8:11]
	v_lshlrev_b32_e32 v20, 16, v36
	v_mfma_f32_4x4x1_16b_f32 v[12:15], v32, v116, v[12:15]
	v_mfma_f32_4x4x1_16b_f32 v[16:19], v32, v124, v[16:19]
	v_and_b32_e32 v36, 0xffff0000, v36
	v_mfma_f32_4x4x1_16b_f32 v[4:7], v76, v117, v[4:7]
	v_mfma_f32_4x4x1_16b_f32 v[8:11], v76, v125, v[8:11]
	v_lshlrev_b32_e32 v21, 16, v37
	v_mfma_f32_4x4x1_16b_f32 v[12:15], v80, v117, v[12:15]
	v_mfma_f32_4x4x1_16b_f32 v[16:19], v80, v125, v[16:19]
	v_and_b32_e32 v37, 0xffff0000, v37
	v_mfma_f32_4x4x1_16b_f32 v[4:7], v29, v118, v[4:7]
	v_mfma_f32_4x4x1_16b_f32 v[8:11], v29, v126, v[8:11]
	v_lshlrev_b32_e32 v22, 16, v38
	v_mfma_f32_4x4x1_16b_f32 v[12:15], v33, v118, v[12:15]
	v_mfma_f32_4x4x1_16b_f32 v[16:19], v33, v126, v[16:19]
	v_and_b32_e32 v38, 0xffff0000, v38
	v_mfma_f32_4x4x1_16b_f32 v[4:7], v77, v119, v[4:7]
	v_mfma_f32_4x4x1_16b_f32 v[8:11], v77, v127, v[8:11]
	v_lshlrev_b32_e32 v23, 16, v39
	v_mfma_f32_4x4x1_16b_f32 v[12:15], v81, v119, v[12:15]
	v_mfma_f32_4x4x1_16b_f32 v[16:19], v81, v127, v[16:19]
	v_and_b32_e32 v39, 0xffff0000, v39
	v_mfma_f32_4x4x1_16b_f32 v[4:7], v30, v120, v[4:7]
	v_mfma_f32_4x4x1_16b_f32 v[8:11], v30, v128, v[8:11]
	v_lshlrev_b32_e32 v24, 16, v40
	v_mfma_f32_4x4x1_16b_f32 v[12:15], v34, v120, v[12:15]
	v_mfma_f32_4x4x1_16b_f32 v[16:19], v34, v128, v[16:19]
	v_and_b32_e32 v40, 0xffff0000, v40
	v_mfma_f32_4x4x1_16b_f32 v[4:7], v78, v121, v[4:7]
	v_mfma_f32_4x4x1_16b_f32 v[8:11], v78, v129, v[8:11]
	v_lshlrev_b32_e32 v25, 16, v41
	v_mfma_f32_4x4x1_16b_f32 v[12:15], v82, v121, v[12:15]
	v_mfma_f32_4x4x1_16b_f32 v[16:19], v82, v129, v[16:19]
	v_and_b32_e32 v41, 0xffff0000, v41
	v_mfma_f32_4x4x1_16b_f32 v[4:7], v31, v122, v[4:7]
	v_mfma_f32_4x4x1_16b_f32 v[8:11], v31, v130, v[8:11]
	v_lshlrev_b32_e32 v26, 16, v42
	v_mfma_f32_4x4x1_16b_f32 v[12:15], v35, v122, v[12:15]
	v_mfma_f32_4x4x1_16b_f32 v[16:19], v35, v130, v[16:19]
	v_and_b32_e32 v42, 0xffff0000, v42
	v_mfma_f32_4x4x1_16b_f32 v[4:7], v79, v123, v[4:7]
	v_mfma_f32_4x4x1_16b_f32 v[8:11], v79, v131, v[8:11]
	v_lshlrev_b32_e32 v27, 16, v43
	v_mfma_f32_4x4x1_16b_f32 v[12:15], v83, v123, v[12:15]
	v_mfma_f32_4x4x1_16b_f32 v[16:19], v83, v131, v[16:19]
	v_and_b32_e32 v43, 0xffff0000, v43
	s_add_i32 s1, s13, 14
	s_and_b32 s1, s1, 15
	s_lshl_b32 s1, s1, 12
	s_add_u32 s36, s8, s1
	s_addc_u32 s37, s9, 0
	global_load_dwordx4 v[116:119], v3, s[36:37] offset:0
	global_load_dwordx4 v[120:123], v3, s[36:37] offset:1024
	global_load_dwordx4 v[124:127], v3, s[36:37] offset:2048
	global_load_dwordx4 v[128:131], v3, s[36:37] offset:3072
	s_waitcnt vmcnt(8)
	v_mfma_f32_4x4x1_16b_f32 v[4:7], v20, v84, v[4:7]
	v_mfma_f32_4x4x1_16b_f32 v[8:11], v20, v92, v[8:11]
	v_lshlrev_b32_e32 v28, 16, v44
	v_mfma_f32_4x4x1_16b_f32 v[12:15], v24, v84, v[12:15]
	v_mfma_f32_4x4x1_16b_f32 v[16:19], v24, v92, v[16:19]
	v_and_b32_e32 v44, 0xffff0000, v44
	v_mfma_f32_4x4x1_16b_f32 v[4:7], v36, v85, v[4:7]
	v_mfma_f32_4x4x1_16b_f32 v[8:11], v36, v93, v[8:11]
	v_lshlrev_b32_e32 v29, 16, v45
	v_mfma_f32_4x4x1_16b_f32 v[12:15], v40, v85, v[12:15]
	v_mfma_f32_4x4x1_16b_f32 v[16:19], v40, v93, v[16:19]
	v_and_b32_e32 v45, 0xffff0000, v45
	v_mfma_f32_4x4x1_16b_f32 v[4:7], v21, v86, v[4:7]
	v_mfma_f32_4x4x1_16b_f32 v[8:11], v21, v94, v[8:11]
	v_lshlrev_b32_e32 v30, 16, v46
	v_mfma_f32_4x4x1_16b_f32 v[12:15], v25, v86, v[12:15]
	v_mfma_f32_4x4x1_16b_f32 v[16:19], v25, v94, v[16:19]
	v_and_b32_e32 v46, 0xffff0000, v46
	v_mfma_f32_4x4x1_16b_f32 v[4:7], v37, v87, v[4:7]
	v_mfma_f32_4x4x1_16b_f32 v[8:11], v37, v95, v[8:11]
	v_lshlrev_b32_e32 v31, 16, v47
	v_mfma_f32_4x4x1_16b_f32 v[12:15], v41, v87, v[12:15]
	v_mfma_f32_4x4x1_16b_f32 v[16:19], v41, v95, v[16:19]
	v_and_b32_e32 v47, 0xffff0000, v47
	v_mfma_f32_4x4x1_16b_f32 v[4:7], v22, v88, v[4:7]
	v_mfma_f32_4x4x1_16b_f32 v[8:11], v22, v96, v[8:11]
	v_lshlrev_b32_e32 v32, 16, v48
	v_mfma_f32_4x4x1_16b_f32 v[12:15], v26, v88, v[12:15]
	v_mfma_f32_4x4x1_16b_f32 v[16:19], v26, v96, v[16:19]
	v_and_b32_e32 v48, 0xffff0000, v48
	v_mfma_f32_4x4x1_16b_f32 v[4:7], v38, v89, v[4:7]
	v_mfma_f32_4x4x1_16b_f32 v[8:11], v38, v97, v[8:11]
	v_lshlrev_b32_e32 v33, 16, v49
	v_mfma_f32_4x4x1_16b_f32 v[12:15], v42, v89, v[12:15]
	v_mfma_f32_4x4x1_16b_f32 v[16:19], v42, v97, v[16:19]
	v_and_b32_e32 v49, 0xffff0000, v49
	v_mfma_f32_4x4x1_16b_f32 v[4:7], v23, v90, v[4:7]
	v_mfma_f32_4x4x1_16b_f32 v[8:11], v23, v98, v[8:11]
	v_lshlrev_b32_e32 v34, 16, v50
	v_mfma_f32_4x4x1_16b_f32 v[12:15], v27, v90, v[12:15]
	v_mfma_f32_4x4x1_16b_f32 v[16:19], v27, v98, v[16:19]
	v_and_b32_e32 v50, 0xffff0000, v50
	v_mfma_f32_4x4x1_16b_f32 v[4:7], v39, v91, v[4:7]
	v_mfma_f32_4x4x1_16b_f32 v[8:11], v39, v99, v[8:11]
	v_lshlrev_b32_e32 v35, 16, v51
	v_mfma_f32_4x4x1_16b_f32 v[12:15], v43, v91, v[12:15]
	v_mfma_f32_4x4x1_16b_f32 v[16:19], v43, v99, v[16:19]
	v_and_b32_e32 v51, 0xffff0000, v51
	s_add_i32 s1, s13, 15
	s_and_b32 s1, s1, 15
	s_lshl_b32 s1, s1, 12
	s_add_u32 s36, s8, s1
	s_addc_u32 s37, s9, 0
	global_load_dwordx4 v[84:87], v3, s[36:37] offset:0
	global_load_dwordx4 v[88:91], v3, s[36:37] offset:1024
	global_load_dwordx4 v[92:95], v3, s[36:37] offset:2048
	global_load_dwordx4 v[96:99], v3, s[36:37] offset:3072
	s_waitcnt vmcnt(8)
; __global__ void __launch_bounds__(NWAVES * 64, 2) fwd_megakernel(Args args) {
;     ...
;                     for (int jj = 0; jj < 4; ++jj) pw[q][jj] = *(const u32x4*)(XB + (size_t)(m0 + q) * DM + 512 * jj + 8 * ln); }
; #pragma unroll
;                 for (int q = 0; q < 4; ++q) { float d = 0.f;
; #pragma unroll
;                     for (int jj = 0; jj < 4; ++jj) { const u32x4 w = pw[q][jj];
;                         d += __uint_as_float(w.x << 16) * wreg[8 * jj + 0] + __uint_as_float(w.x & 0xffff0000u) * wreg[8 * jj + 1] + __uint_as_float(w.y << 16) * wreg[8 * jj + 2] + __uint_as_float(w.y & 0xffff0000u) * wreg[8 * jj + 3]
;                            + __uint_as_float(w.z << 16) * wreg[8 * jj + 4] + __uint_as_float(w.z & 0xffff0000u) * wreg[8 * jj + 5] + __uint_as_float(w.w << 16) * wreg[8 * jj + 6] + __uint_as_float(w.w & 0xffff0000u) * wreg[8 * jj + 7]; }
	v_mfma_f32_4x4x1_16b_f32 v[4:7], v28, v100, v[4:7]
	v_mfma_f32_4x4x1_16b_f32 v[8:11], v28, v108, v[8:11]
	v_lshlrev_b32_e32 v20, 16, v52
	v_mfma_f32_4x4x1_16b_f32 v[12:15], v32, v100, v[12:15]
	v_mfma_f32_4x4x1_16b_f32 v[16:19], v32, v108, v[16:19]
	v_and_b32_e32 v52, 0xffff0000, v52
	v_mfma_f32_4x4x1_16b_f32 v[4:7], v44, v101, v[4:7]
	v_mfma_f32_4x4x1_16b_f32 v[8:11], v44, v109, v[8:11]
	v_lshlrev_b32_e32 v21, 16, v53
	v_mfma_f32_4x4x1_16b_f32 v[12:15], v48, v101, v[12:15]
	v_mfma_f32_4x4x1_16b_f32 v[16:19], v48, v109, v[16:19]
	v_and_b32_e32 v53, 0xffff0000, v53
	v_mfma_f32_4x4x1_16b_f32 v[4:7], v29, v102, v[4:7]
	v_mfma_f32_4x4x1_16b_f32 v[8:11], v29, v110, v[8:11]
	v_lshlrev_b32_e32 v22, 16, v54
	v_mfma_f32_4x4x1_16b_f32 v[12:15], v33, v102, v[12:15]
	v_mfma_f32_4x4x1_16b_f32 v[16:19], v33, v110, v[16:19]
	v_and_b32_e32 v54, 0xffff0000, v54
	v_mfma_f32_4x4x1_16b_f32 v[4:7], v45, v103, v[4:7]
	v_mfma_f32_4x4x1_16b_f32 v[8:11], v45, v111, v[8:11]
	v_lshlrev_b32_e32 v23, 16, v55
	v_mfma_f32_4x4x1_16b_f32 v[12:15], v49, v103, v[12:15]
	v_mfma_f32_4x4x1_16b_f32 v[16:19], v49, v111, v[16:19]
	v_and_b32_e32 v55, 0xffff0000, v55
	v_mfma_f32_4x4x1_16b_f32 v[4:7], v30, v104, v[4:7]
	v_mfma_f32_4x4x1_16b_f32 v[8:11], v30, v112, v[8:11]
	v_lshlrev_b32_e32 v24, 16, v56
	v_mfma_f32_4x4x1_16b_f32 v[12:15], v34, v104, v[12:15]
	v_mfma_f32_4x4x1_16b_f32 v[16:19], v34, v112, v[16:19]
	v_and_b32_e32 v56, 0xffff0000, v56
	v_mfma_f32_4x4x1_16b_f32 v[4:7], v46, v105, v[4:7]
	v_mfma_f32_4x4x1_16b_f32 v[8:11], v46, v113, v[8:11]
	v_lshlrev_b32_e32 v25, 16, v57
	v_mfma_f32_4x4x1_16b_f32 v[12:15], v50, v105, v[12:15]
	v_mfma_f32_4x4x1_16b_f32 v[16:19], v50, v113, v[16:19]
	v_and_b32_e32 v57, 0xffff0000, v57
	v_mfma_f32_4x4x1_16b_f32 v[4:7], v31, v106, v[4:7]
	v_mfma_f32_4x4x1_16b_f32 v[8:11], v31, v114, v[8:11]
	v_lshlrev_b32_e32 v26, 16, v58
	v_mfma_f32_4x4x1_16b_f32 v[12:15], v35, v106, v[12:15]
	v_mfma_f32_4x4x1_16b_f32 v[16:19], v35, v114, v[16:19]
	v_and_b32_e32 v58, 0xffff0000, v58
	v_mfma_f32_4x4x1_16b_f32 v[4:7], v47, v107, v[4:7]
	v_mfma_f32_4x4x1_16b_f32 v[8:11], v47, v115, v[8:11]
	v_lshlrev_b32_e32 v27, 16, v59
	v_mfma_f32_4x4x1_16b_f32 v[12:15], v51, v107, v[12:15]
	v_mfma_f32_4x4x1_16b_f32 v[16:19], v51, v115, v[16:19]
	v_and_b32_e32 v59, 0xffff0000, v59
	s_waitcnt vmcnt(4)
	v_mfma_f32_4x4x1_16b_f32 v[4:7], v20, v116, v[4:7]
	v_mfma_f32_4x4x1_16b_f32 v[8:11], v20, v124, v[8:11]
	v_lshlrev_b32_e32 v28, 16, v60
	v_mfma_f32_4x4x1_16b_f32 v[12:15], v24, v116, v[12:15]
	v_mfma_f32_4x4x1_16b_f32 v[16:19], v24, v124, v[16:19]
	v_and_b32_e32 v60, 0xffff0000, v60
	v_mfma_f32_4x4x1_16b_f32 v[4:7], v52, v117, v[4:7]
	v_mfma_f32_4x4x1_16b_f32 v[8:11], v52, v125, v[8:11]
	v_lshlrev_b32_e32 v29, 16, v61
	v_mfma_f32_4x4x1_16b_f32 v[12:15], v56, v117, v[12:15]
	v_mfma_f32_4x4x1_16b_f32 v[16:19], v56, v125, v[16:19]
	v_and_b32_e32 v61, 0xffff0000, v61
	v_mfma_f32_4x4x1_16b_f32 v[4:7], v21, v118, v[4:7]
	v_mfma_f32_4x4x1_16b_f32 v[8:11], v21, v126, v[8:11]
	v_lshlrev_b32_e32 v30, 16, v62
	v_mfma_f32_4x4x1_16b_f32 v[12:15], v25, v118, v[12:15]
	v_mfma_f32_4x4x1_16b_f32 v[16:19], v25, v126, v[16:19]
	v_and_b32_e32 v62, 0xffff0000, v62
	v_mfma_f32_4x4x1_16b_f32 v[4:7], v53, v119, v[4:7]
	v_mfma_f32_4x4x1_16b_f32 v[8:11], v53, v127, v[8:11]
	v_lshlrev_b32_e32 v31, 16, v63
	v_mfma_f32_4x4x1_16b_f32 v[12:15], v57, v119, v[12:15]
	v_mfma_f32_4x4x1_16b_f32 v[16:19], v57, v127, v[16:19]
	v_and_b32_e32 v63, 0xffff0000, v63
	v_mfma_f32_4x4x1_16b_f32 v[4:7], v22, v120, v[4:7]
	v_mfma_f32_4x4x1_16b_f32 v[8:11], v22, v128, v[8:11]
	v_lshlrev_b32_e32 v32, 16, v64
	v_mfma_f32_4x4x1_16b_f32 v[12:15], v26, v120, v[12:15]
	v_mfma_f32_4x4x1_16b_f32 v[16:19], v26, v128, v[16:19]
	v_and_b32_e32 v64, 0xffff0000, v64
	v_mfma_f32_4x4x1_16b_f32 v[4:7], v54, v121, v[4:7]
	v_mfma_f32_4x4x1_16b_f32 v[8:11], v54, v129, v[8:11]
	v_lshlrev_b32_e32 v33, 16, v65
	v_mfma_f32_4x4x1_16b_f32 v[12:15], v58, v121, v[12:15]
	v_mfma_f32_4x4x1_16b_f32 v[16:19], v58, v129, v[16:19]
	v_and_b32_e32 v65, 0xffff0000, v65
	v_mfma_f32_4x4x1_16b_f32 v[4:7], v23, v122, v[4:7]
	v_mfma_f32_4x4x1_16b_f32 v[8:11], v23, v130, v[8:11]
	v_lshlrev_b32_e32 v34, 16, v66
	v_mfma_f32_4x4x1_16b_f32 v[12:15], v27, v122, v[12:15]
	v_mfma_f32_4x4x1_16b_f32 v[16:19], v27, v130, v[16:19]
	v_and_b32_e32 v66, 0xffff0000, v66
	v_mfma_f32_4x4x1_16b_f32 v[4:7], v55, v123, v[4:7]
	v_mfma_f32_4x4x1_16b_f32 v[8:11], v55, v131, v[8:11]
	v_lshlrev_b32_e32 v35, 16, v67
	v_mfma_f32_4x4x1_16b_f32 v[12:15], v59, v123, v[12:15]
	v_mfma_f32_4x4x1_16b_f32 v[16:19], v59, v131, v[16:19]
	v_and_b32_e32 v67, 0xffff0000, v67
	s_waitcnt vmcnt(0)
; __device__ __forceinline__ float rs_from_ss(float ss) { return rsqrtf(ss * (1.0f / DM) + RMS_EPS); }
; __global__ void __launch_bounds__(NWAVES * 64, 2) fwd_megakernel(Args args) {
;     ...
;                 for (int q = 0; q < 4; ++q) { float d = 0.f;
; #pragma unroll
;                     for (int jj = 0; jj < 4; ++jj) { const u32x4 w = pw[q][jj];
;                         d += __uint_as_float(w.x << 16) * wreg[8 * jj + 0] + __uint_as_float(w.x & 0xffff0000u) * wreg[8 * jj + 1] + __uint_as_float(w.y << 16) * wreg[8 * jj + 2] + __uint_as_float(w.y & 0xffff0000u) * wreg[8 * jj + 3]
;                            + __uint_as_float(w.z << 16) * wreg[8 * jj + 4] + __uint_as_float(w.z & 0xffff0000u) * wreg[8 * jj + 5] + __uint_as_float(w.w << 16) * wreg[8 * jj + 6] + __uint_as_float(w.w & 0xffff0000u) * wreg[8 * jj + 7]; }
;                     d = wave_sum(d);
;                     if (ln == 0) { const int m = m0 + q; const float f = d * rs_from_ss(sq[q]) + bf; const float lf = fminf(f, 0.f) - log1pf(__expf(-fabsf(f)));
;                         logfb[((size_t)(m / SEQ) * NH + wave) * SEQ + (m % SEQ)] = lf; } }
;             }
	v_mfma_f32_4x4x1_16b_f32 v[4:7], v28, v84, v[4:7]
	v_mfma_f32_4x4x1_16b_f32 v[8:11], v28, v92, v[8:11]
	v_mfma_f32_4x4x1_16b_f32 v[12:15], v32, v84, v[12:15]
	v_mfma_f32_4x4x1_16b_f32 v[16:19], v32, v92, v[16:19]
	v_mfma_f32_4x4x1_16b_f32 v[4:7], v60, v85, v[4:7]
	v_mfma_f32_4x4x1_16b_f32 v[8:11], v60, v93, v[8:11]
	v_mfma_f32_4x4x1_16b_f32 v[12:15], v64, v85, v[12:15]
	v_mfma_f32_4x4x1_16b_f32 v[16:19], v64, v93, v[16:19]
	v_mfma_f32_4x4x1_16b_f32 v[4:7], v29, v86, v[4:7]
	v_mfma_f32_4x4x1_16b_f32 v[8:11], v29, v94, v[8:11]
	v_mfma_f32_4x4x1_16b_f32 v[12:15], v33, v86, v[12:15]
	v_mfma_f32_4x4x1_16b_f32 v[16:19], v33, v94, v[16:19]
	v_mfma_f32_4x4x1_16b_f32 v[4:7], v61, v87, v[4:7]
	v_mfma_f32_4x4x1_16b_f32 v[8:11], v61, v95, v[8:11]
	v_mfma_f32_4x4x1_16b_f32 v[12:15], v65, v87, v[12:15]
	v_mfma_f32_4x4x1_16b_f32 v[16:19], v65, v95, v[16:19]
	v_mfma_f32_4x4x1_16b_f32 v[4:7], v30, v88, v[4:7]
	v_mfma_f32_4x4x1_16b_f32 v[8:11], v30, v96, v[8:11]
	v_mfma_f32_4x4x1_16b_f32 v[12:15], v34, v88, v[12:15]
	v_mfma_f32_4x4x1_16b_f32 v[16:19], v34, v96, v[16:19]
	v_mfma_f32_4x4x1_16b_f32 v[4:7], v62, v89, v[4:7]
	v_mfma_f32_4x4x1_16b_f32 v[8:11], v62, v97, v[8:11]
	v_mfma_f32_4x4x1_16b_f32 v[12:15], v66, v89, v[12:15]
	v_mfma_f32_4x4x1_16b_f32 v[16:19], v66, v97, v[16:19]
	v_mfma_f32_4x4x1_16b_f32 v[4:7], v31, v90, v[4:7]
	v_mfma_f32_4x4x1_16b_f32 v[8:11], v31, v98, v[8:11]
	v_mfma_f32_4x4x1_16b_f32 v[12:15], v35, v90, v[12:15]
	v_mfma_f32_4x4x1_16b_f32 v[16:19], v35, v98, v[16:19]
	v_mfma_f32_4x4x1_16b_f32 v[4:7], v63, v91, v[4:7]
	v_mfma_f32_4x4x1_16b_f32 v[8:11], v63, v99, v[8:11]
	v_mfma_f32_4x4x1_16b_f32 v[12:15], v67, v91, v[12:15]
	v_mfma_f32_4x4x1_16b_f32 v[16:19], v67, v99, v[16:19]
	v_lshrrev_b32_e32 v20, 3, v168
	v_and_b32_e32 v21, 7, v168
	v_lshlrev_b32_e32 v22, 2, v20
	v_lshlrev_b32_e32 v23, 2, v21
	s_lshl_b32 s5, s12, 3
	s_add_u32 s5, s5, s4
	s_lshl_b32 s1, s5, 2
	s_add_u32 s1, s1, 0x10000
	s_add_u32 s8, s60, s1
	s_addc_u32 s9, s61, 0
	global_load_dword v24, v22, s[8:9]
	global_load_dword v25, v23, s[16:17]
	s_lshl_b32 s1, s12, 12
	s_add_u32 s1, s1, 0x10000
	v_lshlrev_b32_e32 v26, 2, v168
	v_add_u32_e32 v26, s1, v26
	s_nop 7
	ds_write_b32 v26, v4 offset:0
	ds_write_b32 v26, v5 offset:256
	ds_write_b32 v26, v6 offset:512
	ds_write_b32 v26, v7 offset:768
	ds_write_b32 v26, v8 offset:1024
	ds_write_b32 v26, v9 offset:1280
	ds_write_b32 v26, v10 offset:1536
	ds_write_b32 v26, v11 offset:1792
	ds_write_b32 v26, v12 offset:2048
	ds_write_b32 v26, v13 offset:2304
	ds_write_b32 v26, v14 offset:2560
	ds_write_b32 v26, v15 offset:2816
	ds_write_b32 v26, v16 offset:3072
	ds_write_b32 v26, v17 offset:3328
	ds_write_b32 v26, v18 offset:3584
	ds_write_b32 v26, v19 offset:3840
	v_lshrrev_b32_e32 v27, 2, v20
	v_lshrrev_b32_e32 v28, 2, v21
	v_lshl_or_b32 v27, v27, 1, v28
	v_and_b32_e32 v28, 3, v20
	v_lshl_or_b32 v27, v27, 2, v28
	v_and_b32_e32 v28, 3, v21
	v_lshlrev_b32_e32 v28, 2, v28
	v_lshl_or_b32 v27, v27, 8, v28
	v_add_u32_e32 v27, s1, v27
	s_waitcnt lgkmcnt(0)
	ds_read_b32 v36, v27 offset:0
	ds_read_b32 v37, v27 offset:16
	ds_read_b32 v38, v27 offset:32
	ds_read_b32 v39, v27 offset:48
	ds_read_b32 v40, v27 offset:64
	ds_read_b32 v41, v27 offset:80
	ds_read_b32 v42, v27 offset:96
	ds_read_b32 v43, v27 offset:112
	ds_read_b32 v44, v27 offset:128
	ds_read_b32 v45, v27 offset:144
	ds_read_b32 v46, v27 offset:160
	ds_read_b32 v47, v27 offset:176
	ds_read_b32 v48, v27 offset:192
	ds_read_b32 v49, v27 offset:208
	ds_read_b32 v50, v27 offset:224
	ds_read_b32 v51, v27 offset:240
	s_lshr_b32 s1, s5, 11
	s_lshl_b32 s1, s1, 16
	s_and_b32 s5, s5, 0x7ff
	s_lshl_b32 s5, s5, 2
	s_add_u32 s1, s1, s5
	s_add_u32 s1, s1, 0x80000
	s_add_u32 s8, s60, s1
	s_addc_u32 s9, s61, 0
	v_lshl_or_b32 v29, v21, 13, v22
	s_waitcnt lgkmcnt(0)
	v_add_f32_e32 v36, v36, v44
	v_add_f32_e32 v37, v37, v45
	v_add_f32_e32 v38, v38, v46
	v_add_f32_e32 v39, v39, v47
	v_add_f32_e32 v40, v40, v48
	v_add_f32_e32 v41, v41, v49
	v_add_f32_e32 v42, v42, v50
	v_add_f32_e32 v43, v43, v51
	v_add_f32_e32 v36, v36, v40
	v_add_f32_e32 v37, v37, v41
	v_add_f32_e32 v38, v38, v42
	v_add_f32_e32 v39, v39, v43
	v_add_f32_e32 v36, v36, v38
	v_add_f32_e32 v37, v37, v39
	v_add_f32_e32 v36, v36, v37
	s_waitcnt vmcnt(0)
	v_fmamk_f32 v24, v24, 0x3a000000, v172
	v_rsq_f32_e32 v24, v24
	s_nop 0
	v_fma_f32 v30, v36, v24, v25
	v_mul_f32_e64 v31, |v30|, s18
	v_exp_f32_e32 v31, v31
	s_nop 0
	v_add_f32_e32 v32, 1.0, v31
	v_add_f32_e32 v33, -1.0, v32
	v_sub_f32_e32 v33, v33, v31
	v_log_f32_e32 v34, v32
	v_rcp_f32_e32 v35, v32
	v_mov_b32_e32 v37, 0x3eaaaaab
	v_fmac_f32_e32 v37, 0xbe800000, v31
	v_mul_f32_e32 v34, s19, v34
	v_fma_f32 v34, -v33, v35, v34
	v_fma_f32 v37, v31, v37, -0.5
	v_fma_f32 v37, v31, v37, 1.0
	v_mul_f32_e32 v37, v31, v37
	v_cmp_gt_f32_e32 vcc, 0x3c800000, v31
	v_min_f32_e32 v38, 0, v30
	s_nop 0
	v_cndmask_b32_e32 v34, v34, v37, vcc
	v_sub_f32_e32 v38, v38, v34
	global_store_dword v29, v38, s[8:9]
	s_lshl_b32 s5, s21, 4
	s_add_i32 s4, s4, s5
	s_cmpk_gt_i32 s4, 0x3fff
	s_cbranch_scc0 .Llg_trip
	s_waitcnt lgkmcnt(0)
	s_barrier
